# P4L: P4 epilogue residual loads prefetched (blocks 0-3 up front, 4-7 rolling, counted waits); P5E store-data WAR wait state restored; hoister keeps wait states
# baseline (speedup 1.0000x reference)
; __device__ __forceinline__ u32x4 pack8(f32x4 a, f32x4 b) { u32x4 w; w.x = cvt_pk_bf16(a[0], a[1]); w.y = cvt_pk_bf16(a[2], a[3]); w.z = cvt_pk_bf16(b[0], b[1]); w.w = cvt_pk_bf16(b[2], b[3]); return w; }
;     __device__ __forceinline__ void operator()(const f32x4 (&acc)[2][2][4][2], const pg8::Unit& u, int wr, int wc, int fr, int fq) const {
; #pragma unroll
;         for (int ai = 0; ai < 2; ++ai)
; #pragma unroll
;             for (int m = 0; m < 4; ++m) { const int row = u.pm * 256 + ai * 128 + wr * 64 + m * 16 + fr; float ss = 0.f;
;                 const float* xrow = row < MP ? xp + (size_t)row * D : xs + (size_t)(row - MP) * D;
; #pragma unroll
;                 for (int bj = 0; bj < 2; ++bj) { const int col = u.pn * 256 + bj * 128 + wc * 32 + 8 * fq;
;                     f32x4 v0 = acc[ai][bj][m][0] + *(const f32x4*)(xrow + col), v1 = acc[ai][bj][m][1] + *(const f32x4*)(xrow + col + 4);
;                     ss += (v0[0] * v0[0] + v0[1] * v0[1]) + (v0[2] * v0[2] + v0[3] * v0[3]) + (v1[0] * v1[0] + v1[1] * v1[1]) + (v1[2] * v1[2] + v1[3] * v1[3]);
;                     *(u32x4*)(X2B + (size_t)row * D + col) = pack8(v0, v1); }
;                 ss += __shfl_xor(ss, 16); ss += __shfl_xor(ss, 32);
;                 if (fq == 0) atomicAdd(rss + row, ss); }
;     }
.LBB0_742:
	v_lshl_add_u32 v152, s24, 4, v133
	v_cmp_lt_i32_e32 vcc, s51, v152
	s_and_saveexec_b64 s[24:25], vcc
	s_xor_b64 s[24:25], exec, s[24:25]
	v_add_u32_e32 v140, 0xffffc000, v152
	v_lshlrev_b64 v[150:151], 12, v[140:141]
	v_lshl_add_u64 v[154:155], s[54:55], 0, v[150:151]
	v_mov_b32_e32 v153, v141
	s_andn2_saveexec_b64 s[24:25], s[24:25]
	v_ashrrev_i32_e32 v153, 31, v152
	v_lshlrev_b64 v[150:151], 12, v[152:153]
	v_lshl_add_u64 v[154:155], s[52:53], 0, v[150:151]
	s_or_b64 exec, exec, s[24:25]
	v_lshl_or_b32 v150, s22, 8, v156
	v_ashrrev_i32_e32 v151, 31, v150
	v_lshl_add_u64 v[154:155], v[150:151], 2, v[154:155]
	v_mov_b64_e32 v[246:247], v[154:155]
	s_sub_u32 s26, s54, s52
	s_subb_u32 s27, s55, s53
	s_sub_u32 s26, s26, 0x4000000
	s_subb_u32 s27, s27, 0
	v_cmp_lt_i32_e64 s[30:31], s51, v152
	v_mov_b32_e32 v253, s26
	v_mov_b32_e32 v255, s27
	global_load_dwordx4 v[174:177], v[246:247], off
	global_load_dwordx4 v[178:181], v[246:247], off offset:16
	global_load_dwordx4 v[182:185], v[246:247], off offset:512
	global_load_dwordx4 v[186:189], v[246:247], off offset:528
	v_add_u32_e32 v252, 16, v152
	v_cmp_lt_i32_e32 vcc, s51, v252
	s_andn2_b64 vcc, vcc, s[30:31]
	s_mov_b64 s[28:29], 0x10000
	v_cndmask_b32_e32 v250, 0, v253, vcc
	v_cndmask_b32_e32 v251, 0, v255, vcc
	v_lshl_add_u64 v[248:249], v[246:247], 0, s[28:29]
	v_lshl_add_u64 v[248:249], v[248:249], 0, v[250:251]
	global_load_dwordx4 v[190:193], v[248:249], off
	global_load_dwordx4 v[194:197], v[248:249], off offset:16
	global_load_dwordx4 v[198:201], v[248:249], off offset:512
	global_load_dwordx4 v[202:205], v[248:249], off offset:528
	v_add_u32_e32 v252, 32, v152
	v_cmp_lt_i32_e32 vcc, s51, v252
	s_andn2_b64 vcc, vcc, s[30:31]
	s_mov_b64 s[28:29], 0x20000
	v_cndmask_b32_e32 v250, 0, v253, vcc
	v_cndmask_b32_e32 v251, 0, v255, vcc
	v_lshl_add_u64 v[248:249], v[246:247], 0, s[28:29]
	v_lshl_add_u64 v[248:249], v[248:249], 0, v[250:251]
	global_load_dwordx4 v[206:209], v[248:249], off
	global_load_dwordx4 v[210:213], v[248:249], off offset:16
	global_load_dwordx4 v[214:217], v[248:249], off offset:512
	global_load_dwordx4 v[218:221], v[248:249], off offset:528
	v_add_u32_e32 v252, 48, v152
	v_cmp_lt_i32_e32 vcc, s51, v252
	s_andn2_b64 vcc, vcc, s[30:31]
	s_mov_b64 s[28:29], 0x30000
	v_cndmask_b32_e32 v250, 0, v253, vcc
	v_cndmask_b32_e32 v251, 0, v255, vcc
	v_lshl_add_u64 v[248:249], v[246:247], 0, s[28:29]
	v_lshl_add_u64 v[248:249], v[248:249], 0, v[250:251]
	global_load_dwordx4 v[222:225], v[248:249], off
	global_load_dwordx4 v[226:229], v[248:249], off offset:16
	global_load_dwordx4 v[238:241], v[248:249], off offset:512
	global_load_dwordx4 v[242:245], v[248:249], off offset:528
	s_nop 0
	v_lshlrev_b64 v[170:171], 11, v[152:153]
	v_lshl_add_u64 v[170:171], s[6:7], 0, v[170:171]
	v_lshl_add_u64 v[170:171], v[150:151], 1, v[170:171]
	s_waitcnt vmcnt(14)
	v_pk_add_f32 v[126:127], v[126:127], v[176:177]
	v_pk_add_f32 v[172:173], v[124:125], v[174:175]
	v_pk_add_f32 v[168:169], v[122:123], v[180:181]
	v_pk_add_f32 v[166:167], v[120:121], v[178:179]
	v_cvt_pk_bf16_f32 v120, v172, v173
	v_cvt_pk_bf16_f32 v121, v126, v127
	v_mul_f32_e32 v140, v173, v173
	v_cvt_pk_bf16_f32 v122, v166, v167
	v_cvt_pk_bf16_f32 v123, v168, v169
	global_store_dwordx4 v[170:171], v[120:123], off
	s_nop 0
	s_nop 0
	s_nop 0
	v_mul_f32_e32 v127, v127, v127
	v_and_b32_e32 v121, 64, v160
	v_mul_f32_e32 v154, v167, v167
	v_fmac_f32_e32 v140, v172, v172
	v_fmac_f32_e32 v127, v126, v126
	v_xor_b32_e32 v120, 16, v160
	v_add_u32_e32 v121, 64, v121
	v_mul_f32_e32 v155, v169, v169
	v_fmac_f32_e32 v154, v166, v166
	v_add_f32_e32 v126, v140, v127
	v_cmp_lt_i32_e32 vcc, v120, v121
	v_fmac_f32_e32 v155, v168, v168
	v_add_f32_e32 v126, v126, v154
	v_cndmask_b32_e32 v120, v160, v120, vcc
	v_add_f32_e32 v126, v155, v126
	v_lshlrev_b32_e32 v120, 2, v120
	s_waitcnt vmcnt(13)
	v_pk_add_f32 v[118:119], v[118:119], v[184:185]
	v_pk_add_f32 v[116:117], v[116:117], v[182:183]
	s_waitcnt vmcnt(13)
	v_pk_add_f32 v[124:125], v[112:113], v[186:187]
	v_mul_f32_e32 v112, v117, v117
	v_mul_f32_e32 v113, v119, v119
	v_pk_add_f32 v[114:115], v[114:115], v[188:189]
	v_mul_f32_e32 v122, v125, v125
	v_fmac_f32_e32 v112, v116, v116
	v_fmac_f32_e32 v113, v118, v118
	v_mul_f32_e32 v123, v115, v115
	v_fmac_f32_e32 v122, v124, v124
	v_add_f32_e32 v112, v112, v113
	v_fmac_f32_e32 v123, v114, v114
	v_add_f32_e32 v112, v112, v122
	v_add_f32_e32 v112, v123, v112
	v_add_f32_e32 v112, v126, v112
	ds_bpermute_b32 v113, v120, v112
	v_xor_b32_e32 v122, 32, v160
	v_cmp_lt_i32_e32 vcc, v122, v121
	s_waitcnt lgkmcnt(0)
	v_add_f32_e32 v112, v112, v113
	v_cndmask_b32_e32 v121, v160, v122, vcc
	v_cvt_pk_bf16_f32 v122, v116, v117
	v_lshlrev_b32_e32 v116, 2, v121
	ds_bpermute_b32 v113, v116, v112
	v_cvt_pk_bf16_f32 v123, v118, v119
	v_cvt_pk_bf16_f32 v124, v124, v125
	v_cvt_pk_bf16_f32 v125, v114, v115
	global_store_dwordx4 v[170:171], v[122:125], off offset:256
	s_and_saveexec_b64 s[22:23], s[2:3]
	s_cbranch_execz .LBB0_748
	v_lshl_add_u64 v[114:115], v[152:153], 2, s[8:9]
	s_waitcnt lgkmcnt(0)
	v_add_f32_e32 v112, v112, v113
	global_atomic_add_f32 v[114:115], v112, off
; __device__ __forceinline__ u32x4 pack8(f32x4 a, f32x4 b) { u32x4 w; w.x = cvt_pk_bf16(a[0], a[1]); w.y = cvt_pk_bf16(a[2], a[3]); w.z = cvt_pk_bf16(b[0], b[1]); w.w = cvt_pk_bf16(b[2], b[3]); return w; }
;     __device__ __forceinline__ void operator()(const f32x4 (&acc)[2][2][4][2], const pg8::Unit& u, int wr, int wc, int fr, int fq) const {
;     ...
;             for (int m = 0; m < 4; ++m) { const int row = u.pm * 256 + ai * 128 + wr * 64 + m * 16 + fr; float ss = 0.f;
;                 const float* xrow = row < MP ? xp + (size_t)row * D : xs + (size_t)(row - MP) * D;
; #pragma unroll
;                 for (int bj = 0; bj < 2; ++bj) { const int col = u.pn * 256 + bj * 128 + wc * 32 + 8 * fq;
;                     f32x4 v0 = acc[ai][bj][m][0] + *(const f32x4*)(xrow + col), v1 = acc[ai][bj][m][1] + *(const f32x4*)(xrow + col + 4);
;                     ss += (v0[0] * v0[0] + v0[1] * v0[1]) + (v0[2] * v0[2] + v0[3] * v0[3]) + (v1[0] * v1[0] + v1[1] * v1[1]) + (v1[2] * v1[2] + v1[3] * v1[3]);
;                     *(u32x4*)(X2B + (size_t)row * D + col) = pack8(v0, v1); }
;                 ss += __shfl_xor(ss, 16); ss += __shfl_xor(ss, 32);
;                 if (fq == 0) atomicAdd(rss + row, ss); }
.LBB0_748:
	s_or_b64 exec, exec, s[22:23]
	s_waitcnt lgkmcnt(0)
	v_add_u32_e32 v112, 16, v152
	v_cmp_lt_i32_e32 vcc, s51, v112
	s_and_saveexec_b64 s[22:23], vcc
	s_xor_b64 s[22:23], exec, s[22:23]
	v_add_u32_e32 v140, 0xffffc010, v152
	v_lshlrev_b64 v[114:115], 12, v[140:141]
	v_lshl_add_u64 v[114:115], s[54:55], 0, v[114:115]
	v_mov_b32_e32 v113, v141
	s_andn2_saveexec_b64 s[22:23], s[22:23]
	v_ashrrev_i32_e32 v113, 31, v112
	v_lshlrev_b64 v[114:115], 12, v[112:113]
	v_lshl_add_u64 v[114:115], s[52:53], 0, v[114:115]
	s_or_b64 exec, exec, s[22:23]
	v_lshl_add_u64 v[114:115], v[150:151], 2, v[114:115]
	v_add_u32_e32 v252, 128, v152
	v_cmp_lt_i32_e32 vcc, s51, v252
	s_andn2_b64 vcc, vcc, s[30:31]
	s_mov_b64 s[28:29], 0x80000
	v_cndmask_b32_e32 v250, 0, v253, vcc
	v_cndmask_b32_e32 v251, 0, v255, vcc
	v_lshl_add_u64 v[248:249], v[246:247], 0, s[28:29]
	v_lshl_add_u64 v[248:249], v[248:249], 0, v[250:251]
	global_load_dwordx4 v[174:177], v[248:249], off
	global_load_dwordx4 v[178:181], v[248:249], off offset:16
	global_load_dwordx4 v[182:185], v[248:249], off offset:512
	global_load_dwordx4 v[186:189], v[248:249], off offset:528
	s_nop 0
	v_lshlrev_b64 v[118:119], 11, v[112:113]
	v_lshl_add_u64 v[118:119], s[6:7], 0, v[118:119]
	v_lshl_add_u64 v[118:119], v[150:151], 1, v[118:119]
	s_waitcnt vmcnt(16)
	v_pk_add_f32 v[124:125], v[110:111], v[192:193]
	v_pk_add_f32 v[122:123], v[108:109], v[190:191]
	s_waitcnt vmcnt(16)
	v_pk_add_f32 v[126:127], v[106:107], v[196:197]
	v_pk_add_f32 v[154:155], v[104:105], v[194:195]
	v_cvt_pk_bf16_f32 v104, v122, v123
	v_cvt_pk_bf16_f32 v105, v124, v125
	v_mul_f32_e32 v121, v127, v127
	v_cvt_pk_bf16_f32 v106, v154, v155
	v_cvt_pk_bf16_f32 v107, v126, v127
	global_store_dwordx4 v[118:119], v[104:107], off
	s_nop 0
	s_nop 0
	s_nop 0
	v_mul_f32_e32 v114, v123, v123
	v_mul_f32_e32 v115, v125, v125
	v_mul_f32_e32 v117, v155, v155
	v_fmac_f32_e32 v114, v122, v122
	v_fmac_f32_e32 v115, v124, v124
	v_fmac_f32_e32 v117, v154, v154
	v_add_f32_e32 v114, v114, v115
	v_fmac_f32_e32 v121, v126, v126
	v_add_f32_e32 v114, v114, v117
	v_add_f32_e32 v114, v121, v114
	s_waitcnt vmcnt(15)
	v_pk_add_f32 v[102:103], v[102:103], v[200:201]
	v_pk_add_f32 v[100:101], v[100:101], v[198:199]
	s_waitcnt vmcnt(15)
	v_pk_add_f32 v[106:107], v[96:97], v[202:203]
	v_mul_f32_e32 v96, v101, v101
	v_mul_f32_e32 v97, v103, v103
	v_pk_add_f32 v[104:105], v[98:99], v[204:205]
	v_mul_f32_e32 v98, v107, v107
	v_fmac_f32_e32 v96, v100, v100
	v_fmac_f32_e32 v97, v102, v102
	v_mul_f32_e32 v99, v105, v105
	v_fmac_f32_e32 v98, v106, v106
	v_add_f32_e32 v96, v96, v97
	v_add_f32_e32 v96, v96, v98
	v_fmac_f32_e32 v99, v104, v104
	v_add_f32_e32 v96, v99, v96
	v_add_f32_e32 v96, v114, v96
	ds_bpermute_b32 v97, v120, v96
	v_cvt_pk_bf16_f32 v98, v100, v101
	v_cvt_pk_bf16_f32 v99, v102, v103
	v_cvt_pk_bf16_f32 v100, v106, v107
	v_cvt_pk_bf16_f32 v101, v104, v105
	s_waitcnt lgkmcnt(0)
	v_add_f32_e32 v96, v96, v97
	ds_bpermute_b32 v97, v116, v96
	global_store_dwordx4 v[118:119], v[98:101], off offset:256
	s_and_saveexec_b64 s[22:23], s[2:3]
	s_cbranch_execz .LBB0_754
	v_lshl_add_u64 v[98:99], v[112:113], 2, s[8:9]
	s_waitcnt lgkmcnt(0)
	v_add_f32_e32 v96, v96, v97
	global_atomic_add_f32 v[98:99], v96, off
.LBB0_754:
	s_or_b64 exec, exec, s[22:23]
	s_waitcnt lgkmcnt(0)
	v_add_u32_e32 v96, 32, v152
	v_cmp_lt_i32_e32 vcc, s51, v96
	s_and_saveexec_b64 s[22:23], vcc
	s_xor_b64 s[22:23], exec, s[22:23]
	v_add_u32_e32 v140, 0xffffc020, v152
	v_lshlrev_b64 v[98:99], 12, v[140:141]
	v_lshl_add_u64 v[98:99], s[54:55], 0, v[98:99]
	v_mov_b32_e32 v97, v141
	s_andn2_saveexec_b64 s[22:23], s[22:23]
	v_ashrrev_i32_e32 v97, 31, v96
	v_lshlrev_b64 v[98:99], 12, v[96:97]
	v_lshl_add_u64 v[98:99], s[52:53], 0, v[98:99]
	s_or_b64 exec, exec, s[22:23]
	v_lshl_add_u64 v[106:107], v[150:151], 2, v[98:99]
	v_add_u32_e32 v252, 144, v152
	v_cmp_lt_i32_e32 vcc, s51, v252
	s_andn2_b64 vcc, vcc, s[30:31]
	s_mov_b64 s[28:29], 0x90000
	v_cndmask_b32_e32 v250, 0, v253, vcc
	v_cndmask_b32_e32 v251, 0, v255, vcc
	v_lshl_add_u64 v[248:249], v[246:247], 0, s[28:29]
	v_lshl_add_u64 v[248:249], v[248:249], 0, v[250:251]
	global_load_dwordx4 v[190:193], v[248:249], off
	global_load_dwordx4 v[194:197], v[248:249], off offset:16
	global_load_dwordx4 v[198:201], v[248:249], off offset:512
	global_load_dwordx4 v[202:205], v[248:249], off offset:528
	s_nop 0
	v_lshlrev_b64 v[108:109], 11, v[96:97]
	v_lshl_add_u64 v[108:109], s[6:7], 0, v[108:109]
	v_lshl_add_u64 v[108:109], v[150:151], 1, v[108:109]
	s_waitcnt vmcnt(18)
	v_pk_add_f32 v[100:101], v[94:95], v[208:209]
	v_pk_add_f32 v[98:99], v[92:93], v[206:207]
	s_waitcnt vmcnt(18)
	v_pk_add_f32 v[104:105], v[90:91], v[212:213]
	v_pk_add_f32 v[102:103], v[88:89], v[210:211]
	v_cvt_pk_bf16_f32 v88, v98, v99
	v_cvt_pk_bf16_f32 v89, v100, v101
	v_mul_f32_e32 v99, v99, v99
	v_cvt_pk_bf16_f32 v90, v102, v103
	v_cvt_pk_bf16_f32 v91, v104, v105
	global_store_dwordx4 v[108:109], v[88:91], off
	s_nop 0
	s_nop 0
	s_nop 0
	v_mul_f32_e32 v101, v101, v101
	v_mul_f32_e32 v103, v103, v103
	v_fmac_f32_e32 v99, v98, v98
	v_fmac_f32_e32 v101, v100, v100
	v_mul_f32_e32 v105, v105, v105
	v_fmac_f32_e32 v103, v102, v102
	v_add_f32_e32 v98, v99, v101
	v_fmac_f32_e32 v105, v104, v104
	v_add_f32_e32 v98, v98, v103
	v_add_f32_e32 v98, v105, v98
	s_waitcnt vmcnt(17)
	v_pk_add_f32 v[86:87], v[86:87], v[216:217]
	v_pk_add_f32 v[84:85], v[84:85], v[214:215]
	s_waitcnt vmcnt(17)
	v_pk_add_f32 v[90:91], v[80:81], v[218:219]
	v_mul_f32_e32 v80, v85, v85
	v_mul_f32_e32 v81, v87, v87
	v_pk_add_f32 v[88:89], v[82:83], v[220:221]
	v_mul_f32_e32 v82, v91, v91
	v_fmac_f32_e32 v80, v84, v84
	v_fmac_f32_e32 v81, v86, v86
	v_mul_f32_e32 v83, v89, v89
	v_fmac_f32_e32 v82, v90, v90
	v_add_f32_e32 v80, v80, v81
	v_add_f32_e32 v80, v80, v82
	v_fmac_f32_e32 v83, v88, v88
	v_add_f32_e32 v80, v83, v80
	v_add_f32_e32 v80, v98, v80
	ds_bpermute_b32 v81, v120, v80
	v_cvt_pk_bf16_f32 v82, v84, v85
	v_cvt_pk_bf16_f32 v83, v86, v87
	v_cvt_pk_bf16_f32 v84, v90, v91
	v_cvt_pk_bf16_f32 v85, v88, v89
	s_waitcnt lgkmcnt(0)
	v_add_f32_e32 v80, v80, v81
	ds_bpermute_b32 v81, v116, v80
	global_store_dwordx4 v[108:109], v[82:85], off offset:256
	s_and_saveexec_b64 s[22:23], s[2:3]
	s_cbranch_execz .LBB0_760
	v_lshl_add_u64 v[82:83], v[96:97], 2, s[8:9]
	s_waitcnt lgkmcnt(0)
	v_add_f32_e32 v80, v80, v81
	global_atomic_add_f32 v[82:83], v80, off
; __device__ __forceinline__ u32x4 pack8(f32x4 a, f32x4 b) { u32x4 w; w.x = cvt_pk_bf16(a[0], a[1]); w.y = cvt_pk_bf16(a[2], a[3]); w.z = cvt_pk_bf16(b[0], b[1]); w.w = cvt_pk_bf16(b[2], b[3]); return w; }
;     __device__ __forceinline__ void operator()(const f32x4 (&acc)[2][2][4][2], const pg8::Unit& u, int wr, int wc, int fr, int fq) const {
;     ...
;             for (int m = 0; m < 4; ++m) { const int row = u.pm * 256 + ai * 128 + wr * 64 + m * 16 + fr; float ss = 0.f;
;                 const float* xrow = row < MP ? xp + (size_t)row * D : xs + (size_t)(row - MP) * D;
; #pragma unroll
;                 for (int bj = 0; bj < 2; ++bj) { const int col = u.pn * 256 + bj * 128 + wc * 32 + 8 * fq;
;                     f32x4 v0 = acc[ai][bj][m][0] + *(const f32x4*)(xrow + col), v1 = acc[ai][bj][m][1] + *(const f32x4*)(xrow + col + 4);
;                     ss += (v0[0] * v0[0] + v0[1] * v0[1]) + (v0[2] * v0[2] + v0[3] * v0[3]) + (v1[0] * v1[0] + v1[1] * v1[1]) + (v1[2] * v1[2] + v1[3] * v1[3]);
;                     *(u32x4*)(X2B + (size_t)row * D + col) = pack8(v0, v1); }
;                 ss += __shfl_xor(ss, 16); ss += __shfl_xor(ss, 32);
;                 if (fq == 0) atomicAdd(rss + row, ss); }
.LBB0_760:
	s_or_b64 exec, exec, s[22:23]
	s_waitcnt lgkmcnt(0)
	v_add_u32_e32 v80, 48, v152
	v_cmp_lt_i32_e32 vcc, s51, v80
	s_and_saveexec_b64 s[22:23], vcc
	s_xor_b64 s[22:23], exec, s[22:23]
	v_add_u32_e32 v140, 0xffffc030, v152
	v_lshlrev_b64 v[82:83], 12, v[140:141]
	v_lshl_add_u64 v[82:83], s[54:55], 0, v[82:83]
	v_mov_b32_e32 v81, v141
	s_andn2_saveexec_b64 s[22:23], s[22:23]
	v_ashrrev_i32_e32 v81, 31, v80
	v_lshlrev_b64 v[82:83], 12, v[80:81]
	v_lshl_add_u64 v[82:83], s[52:53], 0, v[82:83]
	s_or_b64 exec, exec, s[22:23]
	v_lshl_add_u64 v[90:91], v[150:151], 2, v[82:83]
	v_add_u32_e32 v252, 160, v152
	v_cmp_lt_i32_e32 vcc, s51, v252
	s_andn2_b64 vcc, vcc, s[30:31]
	s_mov_b64 s[28:29], 0xa0000
	v_cndmask_b32_e32 v250, 0, v253, vcc
	v_cndmask_b32_e32 v251, 0, v255, vcc
	v_lshl_add_u64 v[248:249], v[246:247], 0, s[28:29]
	v_lshl_add_u64 v[248:249], v[248:249], 0, v[250:251]
	global_load_dwordx4 v[206:209], v[248:249], off
	global_load_dwordx4 v[210:213], v[248:249], off offset:16
	global_load_dwordx4 v[214:217], v[248:249], off offset:512
	global_load_dwordx4 v[218:221], v[248:249], off offset:528
	s_nop 0
	v_lshlrev_b64 v[92:93], 11, v[80:81]
	v_lshl_add_u64 v[92:93], s[6:7], 0, v[92:93]
	v_lshl_add_u64 v[92:93], v[150:151], 1, v[92:93]
	s_waitcnt vmcnt(20)
	v_pk_add_f32 v[84:85], v[78:79], v[224:225]
	v_pk_add_f32 v[82:83], v[76:77], v[222:223]
	s_waitcnt vmcnt(20)
	v_pk_add_f32 v[88:89], v[74:75], v[228:229]
	v_pk_add_f32 v[86:87], v[72:73], v[226:227]
	v_cvt_pk_bf16_f32 v72, v82, v83
	v_cvt_pk_bf16_f32 v73, v84, v85
	v_mul_f32_e32 v83, v83, v83
	v_cvt_pk_bf16_f32 v74, v86, v87
	v_cvt_pk_bf16_f32 v75, v88, v89
	global_store_dwordx4 v[92:93], v[72:75], off
	s_nop 0
	s_nop 0
	s_nop 0
	v_mul_f32_e32 v85, v85, v85
	v_mul_f32_e32 v87, v87, v87
	v_fmac_f32_e32 v83, v82, v82
	v_fmac_f32_e32 v85, v84, v84
	v_mul_f32_e32 v89, v89, v89
	v_fmac_f32_e32 v87, v86, v86
	v_add_f32_e32 v82, v83, v85
	v_fmac_f32_e32 v89, v88, v88
	v_add_f32_e32 v82, v82, v87
	v_add_f32_e32 v82, v89, v82
	s_waitcnt vmcnt(19)
	v_pk_add_f32 v[70:71], v[70:71], v[240:241]
	v_pk_add_f32 v[68:69], v[68:69], v[238:239]
	s_waitcnt vmcnt(19)
	v_pk_add_f32 v[74:75], v[64:65], v[242:243]
	v_mul_f32_e32 v64, v69, v69
	v_mul_f32_e32 v65, v71, v71
	v_pk_add_f32 v[72:73], v[66:67], v[244:245]
	v_mul_f32_e32 v66, v75, v75
	v_fmac_f32_e32 v64, v68, v68
	v_fmac_f32_e32 v65, v70, v70
	v_mul_f32_e32 v67, v73, v73
	v_fmac_f32_e32 v66, v74, v74
	v_add_f32_e32 v64, v64, v65
	v_add_f32_e32 v64, v64, v66
	v_fmac_f32_e32 v67, v72, v72
	v_add_f32_e32 v64, v67, v64
	v_add_f32_e32 v64, v82, v64
	ds_bpermute_b32 v65, v120, v64
	v_cvt_pk_bf16_f32 v66, v68, v69
	v_cvt_pk_bf16_f32 v67, v70, v71
	v_cvt_pk_bf16_f32 v68, v74, v75
	v_cvt_pk_bf16_f32 v69, v72, v73
	s_waitcnt lgkmcnt(0)
	v_add_f32_e32 v64, v64, v65
	ds_bpermute_b32 v65, v116, v64
	global_store_dwordx4 v[92:93], v[66:69], off offset:256
	s_and_saveexec_b64 s[22:23], s[2:3]
	s_cbranch_execz .LBB0_766
	v_lshl_add_u64 v[66:67], v[80:81], 2, s[8:9]
	s_waitcnt lgkmcnt(0)
	v_add_f32_e32 v64, v64, v65
	global_atomic_add_f32 v[66:67], v64, off
.LBB0_766:
	s_or_b64 exec, exec, s[22:23]
	s_waitcnt lgkmcnt(0)
	v_add_u32_e32 v64, 0x80, v152
	v_cmp_lt_i32_e32 vcc, s51, v64
	s_and_saveexec_b64 s[22:23], vcc
	s_xor_b64 s[22:23], exec, s[22:23]
	v_add_u32_e32 v140, 0xffffc080, v152
	v_lshlrev_b64 v[66:67], 12, v[140:141]
	v_lshl_add_u64 v[66:67], s[54:55], 0, v[66:67]
	v_mov_b32_e32 v65, v141
	s_andn2_saveexec_b64 s[22:23], s[22:23]
	v_ashrrev_i32_e32 v65, 31, v64
	v_lshlrev_b64 v[66:67], 12, v[64:65]
	v_lshl_add_u64 v[66:67], s[52:53], 0, v[66:67]
	s_or_b64 exec, exec, s[22:23]
	v_lshl_add_u64 v[74:75], v[150:151], 2, v[66:67]
	v_add_u32_e32 v252, 176, v152
	v_cmp_lt_i32_e32 vcc, s51, v252
	s_andn2_b64 vcc, vcc, s[30:31]
	s_mov_b64 s[28:29], 0xb0000
	v_cndmask_b32_e32 v250, 0, v253, vcc
	v_cndmask_b32_e32 v251, 0, v255, vcc
	v_lshl_add_u64 v[248:249], v[246:247], 0, s[28:29]
	v_lshl_add_u64 v[248:249], v[248:249], 0, v[250:251]
	global_load_dwordx4 v[222:225], v[248:249], off
	global_load_dwordx4 v[226:229], v[248:249], off offset:16
	global_load_dwordx4 v[238:241], v[248:249], off offset:512
	global_load_dwordx4 v[242:245], v[248:249], off offset:528
	s_nop 0
	v_lshlrev_b64 v[76:77], 11, v[64:65]
	v_lshl_add_u64 v[76:77], s[6:7], 0, v[76:77]
	v_lshl_add_u64 v[76:77], v[150:151], 1, v[76:77]
	s_waitcnt vmcnt(20)
	v_pk_add_f32 v[68:69], v[62:63], v[176:177]
	v_pk_add_f32 v[66:67], v[60:61], v[174:175]
	s_waitcnt vmcnt(20)
	v_pk_add_f32 v[72:73], v[58:59], v[180:181]
	v_pk_add_f32 v[70:71], v[56:57], v[178:179]
	v_cvt_pk_bf16_f32 v56, v66, v67
	v_cvt_pk_bf16_f32 v57, v68, v69
	v_mul_f32_e32 v67, v67, v67
	v_cvt_pk_bf16_f32 v58, v70, v71
	v_cvt_pk_bf16_f32 v59, v72, v73
	global_store_dwordx4 v[76:77], v[56:59], off
	s_nop 0
	s_nop 0
	s_nop 0
	v_mul_f32_e32 v69, v69, v69
	v_mul_f32_e32 v71, v71, v71
	v_fmac_f32_e32 v67, v66, v66
	v_fmac_f32_e32 v69, v68, v68
	v_mul_f32_e32 v73, v73, v73
	v_fmac_f32_e32 v71, v70, v70
	v_add_f32_e32 v66, v67, v69
	v_fmac_f32_e32 v73, v72, v72
	v_add_f32_e32 v66, v66, v71
	v_add_f32_e32 v66, v73, v66
	s_waitcnt vmcnt(19)
	v_pk_add_f32 v[54:55], v[54:55], v[184:185]
	v_pk_add_f32 v[52:53], v[52:53], v[182:183]
	s_waitcnt vmcnt(19)
	v_pk_add_f32 v[58:59], v[48:49], v[186:187]
	v_mul_f32_e32 v48, v53, v53
	v_mul_f32_e32 v49, v55, v55
	v_pk_add_f32 v[56:57], v[50:51], v[188:189]
	v_mul_f32_e32 v50, v59, v59
	v_fmac_f32_e32 v48, v52, v52
	v_fmac_f32_e32 v49, v54, v54
	v_mul_f32_e32 v51, v57, v57
	v_fmac_f32_e32 v50, v58, v58
	v_add_f32_e32 v48, v48, v49
	v_add_f32_e32 v48, v48, v50
	v_fmac_f32_e32 v51, v56, v56
	v_add_f32_e32 v48, v51, v48
	v_add_f32_e32 v48, v66, v48
	ds_bpermute_b32 v49, v120, v48
	v_cvt_pk_bf16_f32 v50, v52, v53
	v_cvt_pk_bf16_f32 v51, v54, v55
	v_cvt_pk_bf16_f32 v52, v58, v59
	v_cvt_pk_bf16_f32 v53, v56, v57
	s_waitcnt lgkmcnt(0)
	v_add_f32_e32 v48, v48, v49
	ds_bpermute_b32 v49, v116, v48
	global_store_dwordx4 v[76:77], v[50:53], off offset:256
	s_and_saveexec_b64 s[22:23], s[2:3]
	s_cbranch_execz .LBB0_772
	v_lshl_add_u64 v[50:51], v[64:65], 2, s[8:9]
	s_waitcnt lgkmcnt(0)
	v_add_f32_e32 v48, v48, v49
	global_atomic_add_f32 v[50:51], v48, off
; __device__ __forceinline__ u32x4 pack8(f32x4 a, f32x4 b) { u32x4 w; w.x = cvt_pk_bf16(a[0], a[1]); w.y = cvt_pk_bf16(a[2], a[3]); w.z = cvt_pk_bf16(b[0], b[1]); w.w = cvt_pk_bf16(b[2], b[3]); return w; }
;     __device__ __forceinline__ void operator()(const f32x4 (&acc)[2][2][4][2], const pg8::Unit& u, int wr, int wc, int fr, int fq) const {
;     ...
;             for (int m = 0; m < 4; ++m) { const int row = u.pm * 256 + ai * 128 + wr * 64 + m * 16 + fr; float ss = 0.f;
;                 const float* xrow = row < MP ? xp + (size_t)row * D : xs + (size_t)(row - MP) * D;
; #pragma unroll
;                 for (int bj = 0; bj < 2; ++bj) { const int col = u.pn * 256 + bj * 128 + wc * 32 + 8 * fq;
;                     f32x4 v0 = acc[ai][bj][m][0] + *(const f32x4*)(xrow + col), v1 = acc[ai][bj][m][1] + *(const f32x4*)(xrow + col + 4);
;                     ss += (v0[0] * v0[0] + v0[1] * v0[1]) + (v0[2] * v0[2] + v0[3] * v0[3]) + (v1[0] * v1[0] + v1[1] * v1[1]) + (v1[2] * v1[2] + v1[3] * v1[3]);
;                     *(u32x4*)(X2B + (size_t)row * D + col) = pack8(v0, v1); }
;                 ss += __shfl_xor(ss, 16); ss += __shfl_xor(ss, 32);
;                 if (fq == 0) atomicAdd(rss + row, ss); }
.LBB0_772:
	s_or_b64 exec, exec, s[22:23]
	s_waitcnt lgkmcnt(0)
	v_add_u32_e32 v48, 0x90, v152
	v_cmp_lt_i32_e32 vcc, s51, v48
	s_and_saveexec_b64 s[22:23], vcc
	s_xor_b64 s[22:23], exec, s[22:23]
	v_add_u32_e32 v140, 0xffffc090, v152
	v_lshlrev_b64 v[50:51], 12, v[140:141]
	v_lshl_add_u64 v[50:51], s[54:55], 0, v[50:51]
	v_mov_b32_e32 v49, v141
	s_andn2_saveexec_b64 s[22:23], s[22:23]
	v_ashrrev_i32_e32 v49, 31, v48
	v_lshlrev_b64 v[50:51], 12, v[48:49]
	v_lshl_add_u64 v[50:51], s[52:53], 0, v[50:51]
	s_or_b64 exec, exec, s[22:23]
	v_lshl_add_u64 v[58:59], v[150:151], 2, v[50:51]
	s_nop 0
	s_nop 0
	v_lshlrev_b64 v[60:61], 11, v[48:49]
	v_lshl_add_u64 v[60:61], s[6:7], 0, v[60:61]
	v_lshl_add_u64 v[60:61], v[150:151], 1, v[60:61]
	s_waitcnt vmcnt(16)
	v_pk_add_f32 v[52:53], v[46:47], v[192:193]
	v_pk_add_f32 v[50:51], v[44:45], v[190:191]
	s_waitcnt vmcnt(16)
	v_pk_add_f32 v[56:57], v[42:43], v[196:197]
	v_pk_add_f32 v[54:55], v[40:41], v[194:195]
	v_cvt_pk_bf16_f32 v40, v50, v51
	v_cvt_pk_bf16_f32 v41, v52, v53
	v_mul_f32_e32 v51, v51, v51
	v_cvt_pk_bf16_f32 v42, v54, v55
	v_cvt_pk_bf16_f32 v43, v56, v57
	global_store_dwordx4 v[60:61], v[40:43], off
	s_nop 0
	s_nop 0
	s_nop 0
	v_mul_f32_e32 v53, v53, v53
	v_mul_f32_e32 v55, v55, v55
	v_fmac_f32_e32 v51, v50, v50
	v_fmac_f32_e32 v53, v52, v52
	v_mul_f32_e32 v57, v57, v57
	v_fmac_f32_e32 v55, v54, v54
	v_add_f32_e32 v50, v51, v53
	v_fmac_f32_e32 v57, v56, v56
	v_add_f32_e32 v50, v50, v55
	v_add_f32_e32 v50, v57, v50
	s_waitcnt vmcnt(15)
	v_pk_add_f32 v[38:39], v[38:39], v[200:201]
	v_pk_add_f32 v[36:37], v[36:37], v[198:199]
	s_waitcnt vmcnt(15)
	v_pk_add_f32 v[42:43], v[32:33], v[202:203]
	v_mul_f32_e32 v32, v37, v37
	v_mul_f32_e32 v33, v39, v39
	v_pk_add_f32 v[40:41], v[34:35], v[204:205]
	v_mul_f32_e32 v34, v43, v43
	v_fmac_f32_e32 v32, v36, v36
	v_fmac_f32_e32 v33, v38, v38
	v_mul_f32_e32 v35, v41, v41
	v_fmac_f32_e32 v34, v42, v42
	v_add_f32_e32 v32, v32, v33
	v_add_f32_e32 v32, v32, v34
	v_fmac_f32_e32 v35, v40, v40
	v_add_f32_e32 v32, v35, v32
	v_add_f32_e32 v32, v50, v32
	ds_bpermute_b32 v33, v120, v32
	v_cvt_pk_bf16_f32 v34, v36, v37
	v_cvt_pk_bf16_f32 v35, v38, v39
	v_cvt_pk_bf16_f32 v36, v42, v43
	v_cvt_pk_bf16_f32 v37, v40, v41
	s_waitcnt lgkmcnt(0)
	v_add_f32_e32 v32, v32, v33
	ds_bpermute_b32 v33, v116, v32
	global_store_dwordx4 v[60:61], v[34:37], off offset:256
	s_and_saveexec_b64 s[22:23], s[2:3]
	s_cbranch_execz .LBB0_778
	v_lshl_add_u64 v[34:35], v[48:49], 2, s[8:9]
	s_waitcnt lgkmcnt(0)
	v_add_f32_e32 v32, v32, v33
	global_atomic_add_f32 v[34:35], v32, off
; __device__ __forceinline__ u32x4 pack8(f32x4 a, f32x4 b) { u32x4 w; w.x = cvt_pk_bf16(a[0], a[1]); w.y = cvt_pk_bf16(a[2], a[3]); w.z = cvt_pk_bf16(b[0], b[1]); w.w = cvt_pk_bf16(b[2], b[3]); return w; }
;     __device__ __forceinline__ void operator()(const f32x4 (&acc)[2][2][4][2], const pg8::Unit& u, int wr, int wc, int fr, int fq) const {
;     ...
;             for (int m = 0; m < 4; ++m) { const int row = u.pm * 256 + ai * 128 + wr * 64 + m * 16 + fr; float ss = 0.f;
;                 const float* xrow = row < MP ? xp + (size_t)row * D : xs + (size_t)(row - MP) * D;
; #pragma unroll
;                 for (int bj = 0; bj < 2; ++bj) { const int col = u.pn * 256 + bj * 128 + wc * 32 + 8 * fq;
;                     f32x4 v0 = acc[ai][bj][m][0] + *(const f32x4*)(xrow + col), v1 = acc[ai][bj][m][1] + *(const f32x4*)(xrow + col + 4);
;                     ss += (v0[0] * v0[0] + v0[1] * v0[1]) + (v0[2] * v0[2] + v0[3] * v0[3]) + (v1[0] * v1[0] + v1[1] * v1[1]) + (v1[2] * v1[2] + v1[3] * v1[3]);
;                     *(u32x4*)(X2B + (size_t)row * D + col) = pack8(v0, v1); }
;                 ss += __shfl_xor(ss, 16); ss += __shfl_xor(ss, 32);
;                 if (fq == 0) atomicAdd(rss + row, ss); }
.LBB0_778:
	s_or_b64 exec, exec, s[22:23]
	s_waitcnt lgkmcnt(0)
	v_add_u32_e32 v32, 0xa0, v152
	v_cmp_lt_i32_e32 vcc, s51, v32
	s_and_saveexec_b64 s[22:23], vcc
	s_xor_b64 s[22:23], exec, s[22:23]
	v_add_u32_e32 v140, 0xffffc0a0, v152
	v_lshlrev_b64 v[34:35], 12, v[140:141]
	v_lshl_add_u64 v[34:35], s[54:55], 0, v[34:35]
	v_mov_b32_e32 v33, v141
	s_andn2_saveexec_b64 s[22:23], s[22:23]
	v_ashrrev_i32_e32 v33, 31, v32
	v_lshlrev_b64 v[34:35], 12, v[32:33]
	v_lshl_add_u64 v[34:35], s[52:53], 0, v[34:35]
	s_or_b64 exec, exec, s[22:23]
	v_lshl_add_u64 v[42:43], v[150:151], 2, v[34:35]
	s_nop 0
	s_nop 0
	v_lshlrev_b64 v[44:45], 11, v[32:33]
	v_lshl_add_u64 v[44:45], s[6:7], 0, v[44:45]
	v_lshl_add_u64 v[44:45], v[150:151], 1, v[44:45]
	s_waitcnt vmcnt(12)
	v_pk_add_f32 v[36:37], v[30:31], v[208:209]
	v_pk_add_f32 v[34:35], v[28:29], v[206:207]
	s_waitcnt vmcnt(12)
	v_pk_add_f32 v[40:41], v[26:27], v[212:213]
	v_pk_add_f32 v[38:39], v[24:25], v[210:211]
	v_cvt_pk_bf16_f32 v24, v34, v35
	v_cvt_pk_bf16_f32 v25, v36, v37
	v_mul_f32_e32 v35, v35, v35
	v_cvt_pk_bf16_f32 v26, v38, v39
	v_cvt_pk_bf16_f32 v27, v40, v41
	global_store_dwordx4 v[44:45], v[24:27], off
	s_nop 0
	s_nop 0
	s_nop 0
	v_mul_f32_e32 v37, v37, v37
	v_mul_f32_e32 v39, v39, v39
	v_fmac_f32_e32 v35, v34, v34
	v_fmac_f32_e32 v37, v36, v36
	v_mul_f32_e32 v41, v41, v41
	v_fmac_f32_e32 v39, v38, v38
	v_add_f32_e32 v34, v35, v37
	v_fmac_f32_e32 v41, v40, v40
	v_add_f32_e32 v34, v34, v39
	v_add_f32_e32 v34, v41, v34
	s_waitcnt vmcnt(11)
	v_pk_add_f32 v[22:23], v[22:23], v[216:217]
	v_pk_add_f32 v[20:21], v[20:21], v[214:215]
	s_waitcnt vmcnt(11)
	v_pk_add_f32 v[26:27], v[16:17], v[218:219]
	v_mul_f32_e32 v16, v21, v21
	v_mul_f32_e32 v17, v23, v23
	v_pk_add_f32 v[24:25], v[18:19], v[220:221]
	v_mul_f32_e32 v18, v27, v27
	v_fmac_f32_e32 v16, v20, v20
	v_fmac_f32_e32 v17, v22, v22
	v_mul_f32_e32 v19, v25, v25
	v_fmac_f32_e32 v18, v26, v26
	v_add_f32_e32 v16, v16, v17
	v_add_f32_e32 v16, v16, v18
	v_fmac_f32_e32 v19, v24, v24
	v_add_f32_e32 v16, v19, v16
	v_add_f32_e32 v16, v34, v16
	ds_bpermute_b32 v17, v120, v16
	v_cvt_pk_bf16_f32 v18, v20, v21
	v_cvt_pk_bf16_f32 v19, v22, v23
	v_cvt_pk_bf16_f32 v20, v26, v27
	v_cvt_pk_bf16_f32 v21, v24, v25
	s_waitcnt lgkmcnt(0)
	v_add_f32_e32 v16, v16, v17
	ds_bpermute_b32 v17, v116, v16
	global_store_dwordx4 v[44:45], v[18:21], off offset:256
	s_and_saveexec_b64 s[22:23], s[2:3]
	s_cbranch_execz .LBB0_784
	v_lshl_add_u64 v[18:19], v[32:33], 2, s[8:9]
	s_waitcnt lgkmcnt(0)
	v_add_f32_e32 v16, v16, v17
	global_atomic_add_f32 v[18:19], v16, off
.LBB0_784:
	s_or_b64 exec, exec, s[22:23]
	s_waitcnt lgkmcnt(0)
	v_add_u32_e32 v16, 0xb0, v152
	v_cmp_lt_i32_e32 vcc, s51, v16
	s_and_saveexec_b64 s[22:23], vcc
	s_xor_b64 s[22:23], exec, s[22:23]
	v_add_u32_e32 v140, 0xffffc0b0, v152
	v_lshlrev_b64 v[18:19], 12, v[140:141]
	v_lshl_add_u64 v[18:19], s[54:55], 0, v[18:19]
	v_mov_b32_e32 v17, v141
	s_andn2_saveexec_b64 s[22:23], s[22:23]
	v_ashrrev_i32_e32 v17, 31, v16
	v_lshlrev_b64 v[18:19], 12, v[16:17]
	v_lshl_add_u64 v[18:19], s[52:53], 0, v[18:19]
	s_or_b64 exec, exec, s[22:23]
	v_lshl_add_u64 v[26:27], v[150:151], 2, v[18:19]
	s_nop 0
	s_nop 0
	v_lshlrev_b64 v[28:29], 11, v[16:17]
	v_lshl_add_u64 v[28:29], s[6:7], 0, v[28:29]
	v_lshl_add_u64 v[28:29], v[150:151], 1, v[28:29]
	s_waitcnt vmcnt(8)
	v_pk_add_f32 v[20:21], v[14:15], v[224:225]
	v_pk_add_f32 v[18:19], v[12:13], v[222:223]
	s_waitcnt vmcnt(8)
	v_pk_add_f32 v[24:25], v[10:11], v[228:229]
	v_pk_add_f32 v[22:23], v[8:9], v[226:227]
	v_cvt_pk_bf16_f32 v8, v18, v19
	v_cvt_pk_bf16_f32 v9, v20, v21
	v_mul_f32_e32 v19, v19, v19
	v_cvt_pk_bf16_f32 v10, v22, v23
	v_cvt_pk_bf16_f32 v11, v24, v25
	global_store_dwordx4 v[28:29], v[8:11], off
	s_nop 0
	s_nop 0
	s_nop 0
	v_mul_f32_e32 v21, v21, v21
	v_mul_f32_e32 v23, v23, v23
	v_fmac_f32_e32 v19, v18, v18
	v_fmac_f32_e32 v21, v20, v20
	v_mul_f32_e32 v25, v25, v25
	v_fmac_f32_e32 v23, v22, v22
	v_add_f32_e32 v18, v19, v21
	v_fmac_f32_e32 v25, v24, v24
	v_add_f32_e32 v18, v18, v23
	v_add_f32_e32 v18, v25, v18
	s_waitcnt vmcnt(7)
	v_pk_add_f32 v[6:7], v[6:7], v[240:241]
	v_pk_add_f32 v[4:5], v[4:5], v[238:239]
	s_waitcnt vmcnt(7)
	v_pk_add_f32 v[10:11], v[0:1], v[242:243]
	v_mul_f32_e32 v0, v5, v5
	v_mul_f32_e32 v1, v7, v7
	v_pk_add_f32 v[8:9], v[2:3], v[244:245]
	v_mul_f32_e32 v2, v11, v11
	v_fmac_f32_e32 v0, v4, v4
	v_fmac_f32_e32 v1, v6, v6
	v_mul_f32_e32 v3, v9, v9
	v_fmac_f32_e32 v2, v10, v10
	v_add_f32_e32 v0, v0, v1
	v_add_f32_e32 v0, v0, v2
	v_fmac_f32_e32 v3, v8, v8
	v_add_f32_e32 v0, v3, v0
	v_add_f32_e32 v0, v18, v0
	ds_bpermute_b32 v1, v120, v0
	v_cvt_pk_bf16_f32 v2, v4, v5
	v_cvt_pk_bf16_f32 v3, v6, v7
	v_cvt_pk_bf16_f32 v4, v10, v11
	v_cvt_pk_bf16_f32 v5, v8, v9
	s_waitcnt lgkmcnt(0)
	v_add_f32_e32 v0, v0, v1
	ds_bpermute_b32 v1, v116, v0
	global_store_dwordx4 v[28:29], v[2:5], off offset:256
	s_and_saveexec_b64 s[22:23], s[2:3]
	s_cbranch_execz .LBB0_790
	v_lshl_add_u64 v[2:3], v[16:17], 2, s[8:9]
	s_waitcnt lgkmcnt(0)
	v_add_f32_e32 v0, v0, v1
	global_atomic_add_f32 v[2:3], v0, off

; #define PG8_WAIT_V(n) asm volatile("s_waitcnt vmcnt(" #n ")" ::: "memory")
; #define PG8_BAR __builtin_amdgcn_s_barrier()
; __device__ __forceinline__ u32x4 pack8(f32x4 a, f32x4 b) { u32x4 w; w.x = cvt_pk_bf16(a[0], a[1]); w.y = cvt_pk_bf16(a[2], a[3]); w.z = cvt_pk_bf16(b[0], b[1]); w.w = cvt_pk_bf16(b[2], b[3]); return w; }
; template <class Epi>
; __device__ __forceinline__ void gemm_phase(LAS unsigned char* lds, const Gemm g, const StaticOrder& S, const Epi& E) {
;     ...
;     PG8_WAIT_V(0);
;     PG8_BAR;
;     __device__ __forceinline__ void operator()(const f32x4 (&acc)[2][2][4][2], const pg8::Unit& u, int wr, int wc, int fr, int fq) const {
;     ...
;             for (int m = 0; m < 4; ++m) { const int row = u.pm * 256 + ai * 128 + wr * 64 + m * 16 + fr; float ss = 0.f;
;                 const float* xrow = row < MP ? xp + (size_t)row * D : xs + (size_t)(row - MP) * D;
; #pragma unroll
;                 for (int bj = 0; bj < 2; ++bj) { const int col = u.pn * 256 + bj * 128 + wc * 32 + 8 * fq;
;                     f32x4 v0 = acc[ai][bj][m][0] + *(const f32x4*)(xrow + col), v1 = acc[ai][bj][m][1] + *(const f32x4*)(xrow + col + 4);
;                     ss += (v0[0] * v0[0] + v0[1] * v0[1]) + (v0[2] * v0[2] + v0[3] * v0[3]) + (v1[0] * v1[0] + v1[1] * v1[1]) + (v1[2] * v1[2] + v1[3] * v1[3]);
;                     *(u32x4*)(X2B + (size_t)row * D + col) = pack8(v0, v1); }
;                 ss += __shfl_xor(ss, 16); ss += __shfl_xor(ss, 32);
;                 if (fq == 0) atomicAdd(rss + row, ss); }
.LBB0_793:
	s_waitcnt vmcnt(7)
	v_readlane_b32 s46, v254, 22
	s_barrier
	s_and_b32 s0, s44, 7
	s_lshr_b32 s1, s44, 3
	s_and_b32 s1, s1, 7
	s_lshl_b32 s0, s0, 3
	s_add_i32 s0, s0, s1
	s_mulk_i32 s0, 0x110
	s_addk_i32 s0, 0x100
	s_lshr_b32 s1, s44, 6
	v_readlane_b32 s2, v254, 21
	s_nop 3
	s_lshl_b32 s3, s1, 8
	s_mul_i32 s21, s2, 15360
	s_lshl_b32 s2, s2, 5
	s_add_i32 s3, s3, s2
	s_mov_b32 s4, 0x800
	s_add_u32 s8, s88, 0x3000000
	s_addc_u32 s9, s89, 0
	s_add_u32 s10, s88, 0x1a00000
	s_addc_u32 s11, s89, 0
	s_mov_b64 s[6:7], 0x2000
	s_mov_b64 s[12:13], 64
	v_and_b32_e32 v8, 15, v132
	v_lshrrev_b32_e32 v9, 4, v132
	v_add_u32_e32 v5, s0, v8
	v_lshl_add_u32 v2, v9, 3, s3
	v_lshlrev_b32_e32 v6, 4, v9
	v_lshrrev_b32_e32 v7, 3, v8
	v_lshlrev_b32_e32 v7, 5, v7
	v_xor_b32_e32 v6, v6, v7
	v_lshl_add_u32 v6, v8, 6, v6
	v_add_u32_e32 v6, s21, v6
	v_lshrrev_b32_e32 v36, 2, v132
	v_and_b32_e32 v37, 3, v132
	v_lshrrev_b32_e32 v38, 5, v132
	v_lshlrev_b32_e32 v37, 4, v37
	v_lshlrev_b32_e32 v38, 5, v38
	v_xor_b32_e32 v37, v37, v38
	v_add_u32_e32 v38, s0, v36
	v_lshrrev_b32_e32 v39, 2, v36
	v_and_b32_e32 v40, 3, v36
	v_lshl_add_u32 v39, v39, 3, v40
	v_add_u32_e32 v39, s3, v39
	v_mul_lo_u32 v10, v38, s4
	v_mul_lo_u32 v12, v39, s4
	v_mov_b32_e32 v11, 0
	v_mov_b32_e32 v13, 0
	v_add_u32_e32 v10, v10, v37
	v_add_u32_e32 v12, v12, v37
	v_lshl_add_u64 v[10:11], s[8:9], 0, v[10:11]
	v_lshl_add_u64 v[12:13], s[10:11], 0, v[12:13]
	v_lshl_add_u64 v[14:15], v[12:13], 0, s[6:7]
	s_cmp_lt_u32 s0, 0x4000
	s_cselect_b32 s22, s52, s54
	s_cselect_b32 s23, s53, s55
	s_cselect_b32 s20, 0, 0x4000
	v_subrev_u32_e32 v0, s20, v5
	v_lshlrev_b32_e32 v0, 12, v0
	v_lshl_add_u32 v0, v2, 2, v0
	v_mov_b32_e32 v1, 0
	v_lshl_add_u64 v[0:1], s[22:23], 0, v[0:1]
	global_load_dwordx4 v[120:123], v[0:1], off
	global_load_dwordx4 v[124:127], v[0:1], off offset:16
	v_mov_b32_e32 v16, v230
	v_mov_b32_e32 v17, v231
	v_mov_b32_e32 v18, v232
	v_mov_b32_e32 v19, v233
	v_mov_b32_e32 v20, v234
	v_mov_b32_e32 v21, v235
	v_mov_b32_e32 v22, v236
	v_mov_b32_e32 v23, v237
	s_waitcnt vmcnt(0)
	v_add_f32_e32 v16, v16, v120
	v_add_f32_e32 v17, v17, v121
	v_add_f32_e32 v18, v18, v122
	v_add_f32_e32 v19, v19, v123
	v_add_f32_e32 v20, v20, v124
	v_add_f32_e32 v21, v21, v125
	v_add_f32_e32 v22, v22, v126
	v_add_f32_e32 v23, v23, v127
	v_mul_f32_e32 v144, v16, v16
	v_fmac_f32_e32 v144, v17, v17
	v_fmac_f32_e32 v144, v18, v18
	v_fmac_f32_e32 v144, v19, v19
	v_fmac_f32_e32 v144, v20, v20
	v_fmac_f32_e32 v144, v21, v21
	v_fmac_f32_e32 v144, v22, v22
	v_fmac_f32_e32 v144, v23, v23
	v_cvt_pk_bf16_f32 v136, v16, v17
	v_cvt_pk_bf16_f32 v137, v18, v19
	v_cvt_pk_bf16_f32 v138, v20, v21
	v_cvt_pk_bf16_f32 v139, v22, v23
	s_add_u32 s22, s88, 0x18400000
	s_addc_u32 s23, s89, 0
	v_lshlrev_b32_e32 v0, 11, v5
	v_lshl_add_u32 v0, v2, 1, v0
	v_mov_b32_e32 v1, 0
	v_lshl_add_u64 v[0:1], s[22:23], 0, v[0:1]
	global_store_dwordx4 v[0:1], v[136:139], off
	v_lshlrev_b32_e32 v146, 2, v132
	v_xor_b32_e32 v145, 64, v146
	v_xor_b32_e32 v146, 0x80, v146
	ds_bpermute_b32 v147, v145, v144
	s_add_u32 s22, s88, 0x100000
	s_addc_u32 s23, s89, 0
	v_lshlrev_b32_e32 v0, 2, v5
	v_mov_b32_e32 v1, 0
	v_lshl_add_u64 v[0:1], s[22:23], 0, v[0:1]
	v_cmp_gt_u32_e32 vcc, 16, v132
	s_waitcnt lgkmcnt(0)
	v_add_f32_e32 v144, v144, v147
	ds_bpermute_b32 v147, v146, v144
	s_waitcnt lgkmcnt(0)
	v_add_f32_e32 v144, v144, v147
	s_and_saveexec_b64 s[22:23], vcc
	global_atomic_add_f32 v[0:1], v144, off
	s_or_b64 exec, exec, s[22:23]

; __device__ __forceinline__ float fast_sigmoid(float z) { return __builtin_amdgcn_rcpf(1.f + __builtin_amdgcn_exp2f(-z * L2E)); }
; __device__ __forceinline__ u32x4 pack8(f32x4 a, f32x4 b) { u32x4 w; w.x = cvt_pk_bf16(a[0], a[1]); w.y = cvt_pk_bf16(a[2], a[3]); w.z = cvt_pk_bf16(b[0], b[1]); w.w = cvt_pk_bf16(b[2], b[3]); return w; }
;     __device__ __forceinline__ void operator()(const f32x4 (&acc)[2][2][4][2], const pg8::Unit& u, int wr, int wc, int fr, int fq) const {
; #pragma unroll
;         for (int ai = 0; ai < 2; ++ai)
; #pragma unroll
;             for (int m = 0; m < 4; ++m) { const int row = u.pm * 256 + ai * 128 + wr * 64 + m * 16 + fr;
;                 const float rstd = __builtin_amdgcn_rsqf(rss[row] * (1.f / D) + EPS);
;                 f32x4 h0, h1;
; #pragma unroll
;                 for (int i = 0; i < 4; ++i) { const float g0 = acc[ai][0][m][0][i] * rstd, u0 = acc[ai][1][m][0][i] * rstd, g1 = acc[ai][0][m][1][i] * rstd, u1 = acc[ai][1][m][1][i] * rstd;
;                     h0[i] = g0 * fast_sigmoid(g0) * u0; h1[i] = g1 * fast_sigmoid(g1) * u1; }
;                 *(u32x4*)(HFF + (size_t)row * DFF + u.pn * 128 + wc * 32 + 8 * fq) = pack8(h0, h1); }
;     }
.LBB0_859:
	v_lshl_add_u32 v150, s22, 8, v133
	v_ashrrev_i32_e32 v151, 31, v150
	v_lshl_add_u64 v[156:157], v[150:151], 2, s[6:7]
	global_load_dword v228, v[156:157], off
	global_load_dword v229, v[156:157], off offset:64
	global_load_dword v230, v[156:157], off offset:128
	global_load_dword v231, v[156:157], off offset:192
	global_load_dword v232, v[156:157], off offset:512
	global_load_dword v233, v[156:157], off offset:576
	global_load_dword v234, v[156:157], off offset:640
	global_load_dword v235, v[156:157], off offset:704
	v_mov_b32_e32 v156, v124
	v_mov_b32_e32 v157, v116
	v_mov_b32_e32 v159, v112
	v_mov_b32_e32 v116, v125
	v_mov_b32_e32 v112, v121
	v_mov_b32_e32 v124, v126
	v_mov_b32_e32 v125, v118
	v_mov_b32_e32 v161, v114
	v_mov_b32_e32 v114, v123
	v_mov_b32_e32 v158, v120
	v_mov_b32_e32 v160, v122
	v_mov_b32_e32 v118, v127
	v_or_b32_e32 v126, 16, v150
	v_ashrrev_i32_e32 v127, 31, v126
	v_lshl_add_u64 v[164:165], v[126:127], 2, s[6:7]
	s_lshl_b32 s22, s23, 7
	v_mov_b64_e32 v[120:121], s[8:9]
	s_ashr_i32 s23, s22, 31
	v_mad_i64_i32 v[122:123], s[24:25], v150, s49, v[120:121]
	s_lshl_b64 s[22:23], s[22:23], 1
	v_lshl_add_u64 v[122:123], v[122:123], 0, s[22:23]
	v_lshl_add_u64 v[122:123], v[122:123], 0, s[0:1]
	v_lshl_add_u64 v[122:123], v[122:123], 0, v[140:141]
	s_andn2_b64 vcc, exec, s[2:3]
	s_mov_b64 s[2:3], -1
	s_waitcnt vmcnt(7)
	v_fmamk_f32 v151, v228, 0x3a800000, v155
	v_rsq_f32_e32 v162, v151
	s_nop 0
	v_pk_mul_f32 v[116:117], v[116:117], v[162:163] op_sel_hi:[1,0]
	v_pk_mul_f32 v[112:113], v[112:113], v[162:163] op_sel_hi:[1,0]
	v_pk_mul_f32 v[124:125], v[124:125], v[162:163] op_sel_hi:[1,0]
	v_pk_mul_f32 v[114:115], v[114:115], v[162:163] op_sel_hi:[1,0]
	v_pk_mul_f32 v[156:157], v[156:157], v[162:163] op_sel_hi:[1,0]
	v_pk_mul_f32 v[158:159], v[158:159], v[162:163] op_sel_hi:[1,0]
	v_pk_mul_f32 v[160:161], v[160:161], v[162:163] op_sel_hi:[1,0]
	v_pk_mul_f32 v[118:119], v[118:119], v[162:163] op_sel_hi:[1,0]
	v_mul_f32_e32 v162, 0xbfb8aa3b, v117
	v_mul_f32_e32 v163, 0xbfb8aa3b, v113
	v_mul_f32_e32 v166, 0xbfb8aa3b, v125
	v_mul_f32_e32 v169, 0xbfb8aa3b, v115
	v_mul_f32_e32 v127, 0xbfb8aa3b, v157
	v_mul_f32_e32 v151, 0xbfb8aa3b, v159
	v_mul_f32_e32 v167, 0xbfb8aa3b, v161
	v_mul_f32_e32 v168, 0xbfb8aa3b, v119
	v_exp_f32_e32 v162, v162
	v_exp_f32_e32 v163, v163
	v_exp_f32_e32 v166, v166
	v_exp_f32_e32 v169, v169
	v_exp_f32_e32 v127, v127
	v_exp_f32_e32 v151, v151
	v_exp_f32_e32 v167, v167
	v_exp_f32_e32 v168, v168
	v_add_f32_e32 v162, 1.0, v162
	v_add_f32_e32 v163, 1.0, v163
	v_add_f32_e32 v166, 1.0, v166
	v_add_f32_e32 v169, 1.0, v169
	v_add_f32_e32 v127, 1.0, v127
	v_add_f32_e32 v151, 1.0, v151
	v_add_f32_e32 v167, 1.0, v167
	v_add_f32_e32 v168, 1.0, v168
	v_rcp_f32_e32 v162, v162
	v_rcp_f32_e32 v163, v163
	v_rcp_f32_e32 v166, v166
	v_rcp_f32_e32 v169, v169
	v_rcp_f32_e32 v127, v127
	v_rcp_f32_e32 v151, v151
	v_rcp_f32_e32 v167, v167
	v_rcp_f32_e32 v168, v168
	v_mul_f32_e32 v117, v117, v162
	v_mul_f32_e32 v113, v113, v163
	v_mul_f32_e32 v125, v125, v166
	v_mul_f32_e32 v115, v115, v169
	v_mul_f32_e32 v127, v157, v127
	v_mul_f32_e32 v151, v159, v151
	v_mul_f32_e32 v157, v161, v167
	v_mul_f32_e32 v119, v119, v168
	v_mul_f32_e32 v116, v116, v117
	v_mul_f32_e32 v117, v112, v113
	v_mul_f32_e32 v113, v124, v125
	v_mul_f32_e32 v115, v114, v115
	v_mul_f32_e32 v127, v156, v127
	v_mul_f32_e32 v151, v158, v151
	v_mul_f32_e32 v124, v160, v157
	v_mul_f32_e32 v118, v118, v119
	v_cvt_pk_bf16_f32 v112, v127, v116
	v_cvt_pk_bf16_f32 v113, v113, v118
	v_cvt_pk_bf16_f32 v114, v151, v117
	v_cvt_pk_bf16_f32 v115, v124, v115
	global_store_dwordx4 v[122:123], v[112:115], off
	s_nop 0
	s_waitcnt vmcnt(7)
	v_fmamk_f32 v116, v229, 0x3a800000, v155
	v_rsq_f32_e32 v116, v116
	v_mov_b32_e32 v113, v100
	v_mov_b32_e32 v114, v104
	v_mov_b32_e32 v115, v96
	v_mov_b32_e32 v100, v109
	v_mov_b32_e32 v96, v105
	v_mov_b32_e32 v104, v110
	v_mov_b32_e32 v105, v102
	v_mov_b32_e32 v109, v98
	v_mov_b32_e32 v98, v107
	v_mov_b32_e32 v112, v108
	v_mov_b32_e32 v108, v106
	v_mov_b32_e32 v102, v111
	v_or_b32_e32 v106, 32, v150
	v_pk_mul_f32 v[100:101], v[100:101], v[116:117] op_sel_hi:[1,0]
	v_pk_mul_f32 v[96:97], v[96:97], v[116:117] op_sel_hi:[1,0]
	v_pk_mul_f32 v[104:105], v[104:105], v[116:117] op_sel_hi:[1,0]
	v_pk_mul_f32 v[98:99], v[98:99], v[116:117] op_sel_hi:[1,0]
	v_mad_i64_i32 v[110:111], s[24:25], v126, s49, v[120:121]
	v_ashrrev_i32_e32 v107, 31, v106
	v_pk_mul_f32 v[112:113], v[112:113], v[116:117] op_sel_hi:[1,0]
	v_pk_mul_f32 v[114:115], v[114:115], v[116:117] op_sel_hi:[1,0]
	v_pk_mul_f32 v[108:109], v[108:109], v[116:117] op_sel_hi:[1,0]
	v_pk_mul_f32 v[102:103], v[102:103], v[116:117] op_sel_hi:[1,0]
	v_mul_f32_e32 v117, 0xbfb8aa3b, v101
	v_mul_f32_e32 v122, 0xbfb8aa3b, v97
	v_mul_f32_e32 v123, 0xbfb8aa3b, v105
	v_mul_f32_e32 v126, 0xbfb8aa3b, v99
	v_lshl_add_u64 v[118:119], v[106:107], 2, s[6:7]
	v_mul_f32_e32 v107, 0xbfb8aa3b, v113
	v_mul_f32_e32 v116, 0xbfb8aa3b, v115
	v_mul_f32_e32 v124, 0xbfb8aa3b, v109
	v_mul_f32_e32 v125, 0xbfb8aa3b, v103
	v_exp_f32_e32 v117, v117
	v_exp_f32_e32 v122, v122
	v_exp_f32_e32 v123, v123
	v_exp_f32_e32 v126, v126
	v_exp_f32_e32 v107, v107
	v_exp_f32_e32 v116, v116
	v_exp_f32_e32 v124, v124
	v_exp_f32_e32 v125, v125
	v_add_f32_e32 v117, 1.0, v117
	v_add_f32_e32 v122, 1.0, v122
	v_add_f32_e32 v123, 1.0, v123
	v_add_f32_e32 v126, 1.0, v126
	v_add_f32_e32 v107, 1.0, v107
	v_add_f32_e32 v116, 1.0, v116
	v_add_f32_e32 v124, 1.0, v124
	v_add_f32_e32 v125, 1.0, v125
	v_rcp_f32_e32 v117, v117
	v_rcp_f32_e32 v122, v122
	v_rcp_f32_e32 v123, v123
	v_rcp_f32_e32 v126, v126
	v_rcp_f32_e32 v107, v107
	v_rcp_f32_e32 v116, v116
	v_rcp_f32_e32 v124, v124
	v_rcp_f32_e32 v125, v125
	v_lshl_add_u64 v[110:111], v[110:111], 0, s[22:23]
	v_lshl_add_u64 v[110:111], v[110:111], 0, s[0:1]
	v_mul_f32_e32 v101, v101, v117
	v_mul_f32_e32 v97, v97, v122
	v_mul_f32_e32 v105, v105, v123
	v_mul_f32_e32 v99, v99, v126
	v_lshl_add_u64 v[110:111], v[110:111], 0, v[140:141]
	v_mul_f32_e32 v107, v113, v107
	v_mul_f32_e32 v113, v115, v116
	v_mul_f32_e32 v109, v109, v124
	v_mul_f32_e32 v103, v103, v125
	v_mul_f32_e32 v100, v100, v101
	v_mul_f32_e32 v101, v96, v97
	v_mul_f32_e32 v97, v104, v105
	v_mul_f32_e32 v99, v98, v99
	v_mul_f32_e32 v107, v112, v107
	v_mul_f32_e32 v112, v114, v113
	v_mul_f32_e32 v104, v108, v109
	v_mul_f32_e32 v102, v102, v103
	v_cvt_pk_bf16_f32 v96, v107, v100
	v_cvt_pk_bf16_f32 v97, v97, v102
	v_cvt_pk_bf16_f32 v98, v112, v101
	v_cvt_pk_bf16_f32 v99, v104, v99
	global_store_dwordx4 v[110:111], v[96:99], off
	s_nop 0
	s_waitcnt vmcnt(7)
; __device__ __forceinline__ float fast_sigmoid(float z) { return __builtin_amdgcn_rcpf(1.f + __builtin_amdgcn_exp2f(-z * L2E)); }
; __device__ __forceinline__ u32x4 pack8(f32x4 a, f32x4 b) { u32x4 w; w.x = cvt_pk_bf16(a[0], a[1]); w.y = cvt_pk_bf16(a[2], a[3]); w.z = cvt_pk_bf16(b[0], b[1]); w.w = cvt_pk_bf16(b[2], b[3]); return w; }
;     __device__ __forceinline__ void operator()(const f32x4 (&acc)[2][2][4][2], const pg8::Unit& u, int wr, int wc, int fr, int fq) const {
; #pragma unroll
;         for (int ai = 0; ai < 2; ++ai)
; #pragma unroll
;             for (int m = 0; m < 4; ++m) { const int row = u.pm * 256 + ai * 128 + wr * 64 + m * 16 + fr;
;                 const float rstd = __builtin_amdgcn_rsqf(rss[row] * (1.f / D) + EPS);
;                 f32x4 h0, h1;
; #pragma unroll
;                 for (int i = 0; i < 4; ++i) { const float g0 = acc[ai][0][m][0][i] * rstd, u0 = acc[ai][1][m][0][i] * rstd, g1 = acc[ai][0][m][1][i] * rstd, u1 = acc[ai][1][m][1][i] * rstd;
;                     h0[i] = g0 * fast_sigmoid(g0) * u0; h1[i] = g1 * fast_sigmoid(g1) * u1; }
;                 *(u32x4*)(HFF + (size_t)row * DFF + u.pn * 128 + wc * 32 + 8 * fq) = pack8(h0, h1); }
;     }
	v_fmamk_f32 v100, v230, 0x3a800000, v155
	v_rsq_f32_e32 v100, v100
	v_mov_b32_e32 v97, v84
	v_mov_b32_e32 v98, v88
	v_mov_b32_e32 v99, v80
	v_mov_b32_e32 v84, v93
	v_mov_b32_e32 v80, v89
	v_mov_b32_e32 v88, v94
	v_mov_b32_e32 v89, v86
	v_mov_b32_e32 v93, v82
	v_mov_b32_e32 v82, v91
	v_mov_b32_e32 v96, v92
	v_mov_b32_e32 v92, v90
	v_mov_b32_e32 v86, v95
	v_or_b32_e32 v90, 48, v150
	v_pk_mul_f32 v[84:85], v[84:85], v[100:101] op_sel_hi:[1,0]
	v_pk_mul_f32 v[80:81], v[80:81], v[100:101] op_sel_hi:[1,0]
	v_pk_mul_f32 v[88:89], v[88:89], v[100:101] op_sel_hi:[1,0]
	v_pk_mul_f32 v[82:83], v[82:83], v[100:101] op_sel_hi:[1,0]
	v_ashrrev_i32_e32 v91, 31, v90
	v_pk_mul_f32 v[96:97], v[96:97], v[100:101] op_sel_hi:[1,0]
	v_pk_mul_f32 v[98:99], v[98:99], v[100:101] op_sel_hi:[1,0]
	v_pk_mul_f32 v[92:93], v[92:93], v[100:101] op_sel_hi:[1,0]
	v_pk_mul_f32 v[86:87], v[86:87], v[100:101] op_sel_hi:[1,0]
	v_mul_f32_e32 v101, 0xbfb8aa3b, v85
	v_mul_f32_e32 v104, 0xbfb8aa3b, v81
	v_mul_f32_e32 v105, 0xbfb8aa3b, v89
	v_mul_f32_e32 v108, 0xbfb8aa3b, v83
	v_mad_i64_i32 v[94:95], s[24:25], v106, s49, v[120:121]
	v_lshl_add_u64 v[102:103], v[90:91], 2, s[6:7]
	v_mul_f32_e32 v91, 0xbfb8aa3b, v97
	v_mul_f32_e32 v100, 0xbfb8aa3b, v99
	v_mul_f32_e32 v106, 0xbfb8aa3b, v93
	v_mul_f32_e32 v107, 0xbfb8aa3b, v87
	v_exp_f32_e32 v101, v101
	v_exp_f32_e32 v104, v104
	v_exp_f32_e32 v105, v105
	v_exp_f32_e32 v108, v108
	v_exp_f32_e32 v91, v91
	v_exp_f32_e32 v100, v100
	v_exp_f32_e32 v106, v106
	v_exp_f32_e32 v107, v107
	v_add_f32_e32 v101, 1.0, v101
	v_add_f32_e32 v104, 1.0, v104
	v_add_f32_e32 v105, 1.0, v105
	v_add_f32_e32 v108, 1.0, v108
	v_add_f32_e32 v91, 1.0, v91
	v_add_f32_e32 v100, 1.0, v100
	v_add_f32_e32 v106, 1.0, v106
	v_add_f32_e32 v107, 1.0, v107
	v_rcp_f32_e32 v101, v101
	v_rcp_f32_e32 v104, v104
	v_rcp_f32_e32 v105, v105
	v_rcp_f32_e32 v108, v108
	v_rcp_f32_e32 v91, v91
	v_rcp_f32_e32 v100, v100
	v_rcp_f32_e32 v106, v106
	v_rcp_f32_e32 v107, v107
	v_lshl_add_u64 v[94:95], v[94:95], 0, s[22:23]
	v_lshl_add_u64 v[94:95], v[94:95], 0, s[0:1]
	v_mul_f32_e32 v85, v85, v101
	v_mul_f32_e32 v81, v81, v104
	v_mul_f32_e32 v89, v89, v105
	v_mul_f32_e32 v83, v83, v108
	v_lshl_add_u64 v[94:95], v[94:95], 0, v[140:141]
	v_mul_f32_e32 v91, v97, v91
	v_mul_f32_e32 v97, v99, v100
	v_mul_f32_e32 v93, v93, v106
	v_mul_f32_e32 v87, v87, v107
	v_mul_f32_e32 v84, v84, v85
	v_mul_f32_e32 v85, v80, v81
	v_mul_f32_e32 v81, v88, v89
	v_mul_f32_e32 v83, v82, v83
	v_mul_f32_e32 v91, v96, v91
	v_mul_f32_e32 v96, v98, v97
	v_mul_f32_e32 v88, v92, v93
	v_mul_f32_e32 v86, v86, v87
	v_cvt_pk_bf16_f32 v80, v91, v84
	v_cvt_pk_bf16_f32 v81, v81, v86
	v_cvt_pk_bf16_f32 v82, v96, v85
	v_cvt_pk_bf16_f32 v83, v88, v83
	global_store_dwordx4 v[94:95], v[80:83], off
	s_nop 0
	s_waitcnt vmcnt(7)
	v_fmamk_f32 v84, v231, 0x3a800000, v155
	v_rsq_f32_e32 v84, v84
	v_mov_b32_e32 v81, v68
	v_mov_b32_e32 v82, v72
	v_mov_b32_e32 v83, v64
	v_mov_b32_e32 v68, v77
	v_mov_b32_e32 v64, v73
	v_mov_b32_e32 v72, v78
	v_mov_b32_e32 v73, v70
	v_mov_b32_e32 v77, v66
	v_mov_b32_e32 v66, v75
	v_mov_b32_e32 v80, v76
	v_mov_b32_e32 v76, v74
	v_mov_b32_e32 v70, v79
	v_add_u32_e32 v74, 0x80, v150
	v_pk_mul_f32 v[68:69], v[68:69], v[84:85] op_sel_hi:[1,0]
	v_pk_mul_f32 v[64:65], v[64:65], v[84:85] op_sel_hi:[1,0]
	v_pk_mul_f32 v[72:73], v[72:73], v[84:85] op_sel_hi:[1,0]
	v_pk_mul_f32 v[66:67], v[66:67], v[84:85] op_sel_hi:[1,0]
	v_ashrrev_i32_e32 v75, 31, v74
	v_pk_mul_f32 v[80:81], v[80:81], v[84:85] op_sel_hi:[1,0]
	v_pk_mul_f32 v[82:83], v[82:83], v[84:85] op_sel_hi:[1,0]
	v_pk_mul_f32 v[76:77], v[76:77], v[84:85] op_sel_hi:[1,0]
	v_pk_mul_f32 v[70:71], v[70:71], v[84:85] op_sel_hi:[1,0]
	v_mul_f32_e32 v85, 0xbfb8aa3b, v69
	v_mul_f32_e32 v88, 0xbfb8aa3b, v65
	v_mul_f32_e32 v89, 0xbfb8aa3b, v73
	v_mul_f32_e32 v92, 0xbfb8aa3b, v67
	v_mad_i64_i32 v[78:79], s[24:25], v90, s49, v[120:121]
	v_lshl_add_u64 v[86:87], v[74:75], 2, s[6:7]
	v_mul_f32_e32 v75, 0xbfb8aa3b, v81
	v_mul_f32_e32 v84, 0xbfb8aa3b, v83
	v_mul_f32_e32 v90, 0xbfb8aa3b, v77
	v_mul_f32_e32 v91, 0xbfb8aa3b, v71
	v_exp_f32_e32 v85, v85
	v_exp_f32_e32 v88, v88
	v_exp_f32_e32 v89, v89
	v_exp_f32_e32 v92, v92
	v_exp_f32_e32 v75, v75
	v_exp_f32_e32 v84, v84
	v_exp_f32_e32 v90, v90
	v_exp_f32_e32 v91, v91
	v_add_f32_e32 v85, 1.0, v85
	v_add_f32_e32 v88, 1.0, v88
	v_add_f32_e32 v89, 1.0, v89
	v_add_f32_e32 v92, 1.0, v92
	v_add_f32_e32 v75, 1.0, v75
	v_add_f32_e32 v84, 1.0, v84
	v_add_f32_e32 v90, 1.0, v90
	v_add_f32_e32 v91, 1.0, v91
	v_rcp_f32_e32 v85, v85
	v_rcp_f32_e32 v88, v88
	v_rcp_f32_e32 v89, v89
	v_rcp_f32_e32 v92, v92
	v_rcp_f32_e32 v75, v75
	v_rcp_f32_e32 v84, v84
	v_rcp_f32_e32 v90, v90
	v_rcp_f32_e32 v91, v91
	v_lshl_add_u64 v[78:79], v[78:79], 0, s[22:23]
	v_lshl_add_u64 v[78:79], v[78:79], 0, s[0:1]
	v_mul_f32_e32 v69, v69, v85
	v_mul_f32_e32 v65, v65, v88
	v_mul_f32_e32 v73, v73, v89
	v_mul_f32_e32 v67, v67, v92
	v_lshl_add_u64 v[78:79], v[78:79], 0, v[140:141]
	v_mul_f32_e32 v75, v81, v75
	v_mul_f32_e32 v81, v83, v84
	v_mul_f32_e32 v77, v77, v90
	v_mul_f32_e32 v71, v71, v91
	v_mul_f32_e32 v68, v68, v69
	v_mul_f32_e32 v69, v64, v65
	v_mul_f32_e32 v65, v72, v73
	v_mul_f32_e32 v67, v66, v67
	v_mul_f32_e32 v75, v80, v75
	v_mul_f32_e32 v80, v82, v81
	v_mul_f32_e32 v72, v76, v77
	v_mul_f32_e32 v70, v70, v71
	v_cvt_pk_bf16_f32 v64, v75, v68
	v_cvt_pk_bf16_f32 v65, v65, v70
	v_cvt_pk_bf16_f32 v66, v80, v69
	v_cvt_pk_bf16_f32 v67, v72, v67
	global_store_dwordx4 v[78:79], v[64:67], off
	s_nop 0
	s_waitcnt vmcnt(7)
; __device__ __forceinline__ float fast_sigmoid(float z) { return __builtin_amdgcn_rcpf(1.f + __builtin_amdgcn_exp2f(-z * L2E)); }
; __device__ __forceinline__ u32x4 pack8(f32x4 a, f32x4 b) { u32x4 w; w.x = cvt_pk_bf16(a[0], a[1]); w.y = cvt_pk_bf16(a[2], a[3]); w.z = cvt_pk_bf16(b[0], b[1]); w.w = cvt_pk_bf16(b[2], b[3]); return w; }
;     __device__ __forceinline__ void operator()(const f32x4 (&acc)[2][2][4][2], const pg8::Unit& u, int wr, int wc, int fr, int fq) const {
; #pragma unroll
;         for (int ai = 0; ai < 2; ++ai)
; #pragma unroll
;             for (int m = 0; m < 4; ++m) { const int row = u.pm * 256 + ai * 128 + wr * 64 + m * 16 + fr;
;                 const float rstd = __builtin_amdgcn_rsqf(rss[row] * (1.f / D) + EPS);
;                 f32x4 h0, h1;
; #pragma unroll
;                 for (int i = 0; i < 4; ++i) { const float g0 = acc[ai][0][m][0][i] * rstd, u0 = acc[ai][1][m][0][i] * rstd, g1 = acc[ai][0][m][1][i] * rstd, u1 = acc[ai][1][m][1][i] * rstd;
;                     h0[i] = g0 * fast_sigmoid(g0) * u0; h1[i] = g1 * fast_sigmoid(g1) * u1; }
;                 *(u32x4*)(HFF + (size_t)row * DFF + u.pn * 128 + wc * 32 + 8 * fq) = pack8(h0, h1); }
;     }
	v_fmamk_f32 v68, v232, 0x3a800000, v155
	v_rsq_f32_e32 v68, v68
	v_mov_b32_e32 v65, v52
	v_mov_b32_e32 v66, v56
	v_mov_b32_e32 v67, v48
	v_mov_b32_e32 v52, v61
	v_mov_b32_e32 v48, v57
	v_mov_b32_e32 v56, v62
	v_mov_b32_e32 v57, v54
	v_mov_b32_e32 v61, v50
	v_mov_b32_e32 v50, v59
	v_mov_b32_e32 v64, v60
	v_mov_b32_e32 v60, v58
	v_mov_b32_e32 v54, v63
	v_add_u32_e32 v58, 0x90, v150
	v_pk_mul_f32 v[52:53], v[52:53], v[68:69] op_sel_hi:[1,0]
	v_pk_mul_f32 v[48:49], v[48:49], v[68:69] op_sel_hi:[1,0]
	v_pk_mul_f32 v[56:57], v[56:57], v[68:69] op_sel_hi:[1,0]
	v_pk_mul_f32 v[50:51], v[50:51], v[68:69] op_sel_hi:[1,0]
	v_ashrrev_i32_e32 v59, 31, v58
	v_pk_mul_f32 v[64:65], v[64:65], v[68:69] op_sel_hi:[1,0]
	v_pk_mul_f32 v[66:67], v[66:67], v[68:69] op_sel_hi:[1,0]
	v_pk_mul_f32 v[60:61], v[60:61], v[68:69] op_sel_hi:[1,0]
	v_pk_mul_f32 v[54:55], v[54:55], v[68:69] op_sel_hi:[1,0]
	v_mul_f32_e32 v69, 0xbfb8aa3b, v53
	v_mul_f32_e32 v72, 0xbfb8aa3b, v49
	v_mul_f32_e32 v73, 0xbfb8aa3b, v57
	v_mul_f32_e32 v76, 0xbfb8aa3b, v51
	v_mad_i64_i32 v[62:63], s[24:25], v74, s49, v[120:121]
	v_lshl_add_u64 v[70:71], v[58:59], 2, s[6:7]
	v_mul_f32_e32 v59, 0xbfb8aa3b, v65
	v_mul_f32_e32 v68, 0xbfb8aa3b, v67
	v_mul_f32_e32 v74, 0xbfb8aa3b, v61
	v_mul_f32_e32 v75, 0xbfb8aa3b, v55
	v_exp_f32_e32 v69, v69
	v_exp_f32_e32 v72, v72
	v_exp_f32_e32 v73, v73
	v_exp_f32_e32 v76, v76
	v_exp_f32_e32 v59, v59
	v_exp_f32_e32 v68, v68
	v_exp_f32_e32 v74, v74
	v_exp_f32_e32 v75, v75
	v_add_f32_e32 v69, 1.0, v69
	v_add_f32_e32 v72, 1.0, v72
	v_add_f32_e32 v73, 1.0, v73
	v_add_f32_e32 v76, 1.0, v76
	v_add_f32_e32 v59, 1.0, v59
	v_add_f32_e32 v68, 1.0, v68
	v_add_f32_e32 v74, 1.0, v74
	v_add_f32_e32 v75, 1.0, v75
	v_rcp_f32_e32 v69, v69
	v_rcp_f32_e32 v72, v72
	v_rcp_f32_e32 v73, v73
	v_rcp_f32_e32 v76, v76
	v_rcp_f32_e32 v59, v59
	v_rcp_f32_e32 v68, v68
	v_rcp_f32_e32 v74, v74
	v_rcp_f32_e32 v75, v75
	v_lshl_add_u64 v[62:63], v[62:63], 0, s[22:23]
	v_lshl_add_u64 v[62:63], v[62:63], 0, s[0:1]
	v_mul_f32_e32 v53, v53, v69
	v_mul_f32_e32 v49, v49, v72
	v_mul_f32_e32 v57, v57, v73
	v_mul_f32_e32 v51, v51, v76
	v_lshl_add_u64 v[62:63], v[62:63], 0, v[140:141]
	v_mul_f32_e32 v59, v65, v59
	v_mul_f32_e32 v65, v67, v68
	v_mul_f32_e32 v61, v61, v74
	v_mul_f32_e32 v55, v55, v75
	v_mul_f32_e32 v52, v52, v53
	v_mul_f32_e32 v53, v48, v49
	v_mul_f32_e32 v49, v56, v57
	v_mul_f32_e32 v51, v50, v51
	v_mul_f32_e32 v59, v64, v59
	v_mul_f32_e32 v64, v66, v65
	v_mul_f32_e32 v56, v60, v61
	v_mul_f32_e32 v54, v54, v55
	v_cvt_pk_bf16_f32 v48, v59, v52
	v_cvt_pk_bf16_f32 v49, v49, v54
	v_cvt_pk_bf16_f32 v50, v64, v53
	v_cvt_pk_bf16_f32 v51, v56, v51
	global_store_dwordx4 v[62:63], v[48:51], off
	s_nop 0
	s_waitcnt vmcnt(7)
	v_fmamk_f32 v52, v233, 0x3a800000, v155
	v_rsq_f32_e32 v52, v52
	v_mov_b32_e32 v49, v36
	v_mov_b32_e32 v50, v40
	v_mov_b32_e32 v51, v32
	v_mov_b32_e32 v36, v45
	v_mov_b32_e32 v32, v41
	v_mov_b32_e32 v40, v46
	v_mov_b32_e32 v41, v38
	v_mov_b32_e32 v45, v34
	v_mov_b32_e32 v34, v43
	v_mov_b32_e32 v48, v44
	v_mov_b32_e32 v44, v42
	v_mov_b32_e32 v38, v47
	v_add_u32_e32 v42, 0xa0, v150
	v_pk_mul_f32 v[36:37], v[36:37], v[52:53] op_sel_hi:[1,0]
	v_pk_mul_f32 v[32:33], v[32:33], v[52:53] op_sel_hi:[1,0]
	v_pk_mul_f32 v[40:41], v[40:41], v[52:53] op_sel_hi:[1,0]
	v_pk_mul_f32 v[34:35], v[34:35], v[52:53] op_sel_hi:[1,0]
	v_ashrrev_i32_e32 v43, 31, v42
	v_pk_mul_f32 v[48:49], v[48:49], v[52:53] op_sel_hi:[1,0]
	v_pk_mul_f32 v[50:51], v[50:51], v[52:53] op_sel_hi:[1,0]
	v_pk_mul_f32 v[44:45], v[44:45], v[52:53] op_sel_hi:[1,0]
	v_pk_mul_f32 v[38:39], v[38:39], v[52:53] op_sel_hi:[1,0]
	v_mul_f32_e32 v53, 0xbfb8aa3b, v37
	v_mul_f32_e32 v56, 0xbfb8aa3b, v33
	v_mul_f32_e32 v57, 0xbfb8aa3b, v41
	v_mul_f32_e32 v60, 0xbfb8aa3b, v35
	v_mad_i64_i32 v[46:47], s[24:25], v58, s49, v[120:121]
	v_lshl_add_u64 v[54:55], v[42:43], 2, s[6:7]
	v_mul_f32_e32 v43, 0xbfb8aa3b, v49
	v_mul_f32_e32 v52, 0xbfb8aa3b, v51
	v_mul_f32_e32 v58, 0xbfb8aa3b, v45
	v_mul_f32_e32 v59, 0xbfb8aa3b, v39
	v_exp_f32_e32 v53, v53
	v_exp_f32_e32 v56, v56
	v_exp_f32_e32 v57, v57
	v_exp_f32_e32 v60, v60
	v_exp_f32_e32 v43, v43
	v_exp_f32_e32 v52, v52
	v_exp_f32_e32 v58, v58
	v_exp_f32_e32 v59, v59
	v_add_f32_e32 v53, 1.0, v53
	v_add_f32_e32 v56, 1.0, v56
	v_add_f32_e32 v57, 1.0, v57
	v_add_f32_e32 v60, 1.0, v60
	v_add_f32_e32 v43, 1.0, v43
	v_add_f32_e32 v52, 1.0, v52
	v_add_f32_e32 v58, 1.0, v58
	v_add_f32_e32 v59, 1.0, v59
	v_rcp_f32_e32 v53, v53
	v_rcp_f32_e32 v56, v56
	v_rcp_f32_e32 v57, v57
	v_rcp_f32_e32 v60, v60
	v_rcp_f32_e32 v43, v43
	v_rcp_f32_e32 v52, v52
	v_rcp_f32_e32 v58, v58
	v_rcp_f32_e32 v59, v59
	v_lshl_add_u64 v[46:47], v[46:47], 0, s[22:23]
	v_lshl_add_u64 v[46:47], v[46:47], 0, s[0:1]
	v_mul_f32_e32 v37, v37, v53
	v_mul_f32_e32 v33, v33, v56
	v_mul_f32_e32 v41, v41, v57
	v_mul_f32_e32 v35, v35, v60
	v_lshl_add_u64 v[46:47], v[46:47], 0, v[140:141]
	v_mul_f32_e32 v43, v49, v43
	v_mul_f32_e32 v49, v51, v52
	v_mul_f32_e32 v45, v45, v58
	v_mul_f32_e32 v39, v39, v59
	v_mul_f32_e32 v36, v36, v37
	v_mul_f32_e32 v37, v32, v33
	v_mul_f32_e32 v33, v40, v41
	v_mul_f32_e32 v35, v34, v35
	v_mul_f32_e32 v43, v48, v43
	v_mul_f32_e32 v48, v50, v49
	v_mul_f32_e32 v40, v44, v45
	v_mul_f32_e32 v38, v38, v39
	v_cvt_pk_bf16_f32 v32, v43, v36
	v_cvt_pk_bf16_f32 v33, v33, v38
	v_cvt_pk_bf16_f32 v34, v48, v37
	v_cvt_pk_bf16_f32 v35, v40, v35
	global_store_dwordx4 v[46:47], v[32:35], off
	s_nop 0
	s_waitcnt vmcnt(7)
; template <class Epi>
; __device__ __forceinline__ void gemm_phase(LAS unsigned char* lds, const Gemm g, const StaticOrder& S, const Epi& E) {
;     ...
;         for (int t = 0; t < nt; t += 2) {
;             if constexpr (Epi::HAS_MID) { if (t == nt / 2) E.mid(acc, cur, wr, wc, fr, fq); }
;             const bool last = (t == nt - 2);
;             const char* a1 = cA + (size_t)(t + 1) * kstep;
;             const char* a2 = last ? nA : cA + (size_t)(t + 2) * kstep; const char* b2 = last ? nB : cB + (size_t)(t + 2) * kstep;
;             const char* a3 = a2 + kstep; const char* b3 = b2 + kstep;
;             PG8_LDB(B0, 0, 0); PG8_LDB(B1, 0, 1); PG8_SCHED; PG8_LDA(At, 0, 0); PG8_STAGE(PG8_SA(1, 1), a1 + hstep, voffA);
;             PG8_WAIT_V(8); PG8_WAIT_L(0); PG8_BAR; PG8_MMA(0, 0, At, B0); PG8_MMA(0, 1, At, B1); PG8_BAR; PG8_SCHED;
;             PG8_LDA(At, 0, 1); PG8_STAGE(PG8_SB(0, 0), b2, voffB); PG8_STAGE(PG8_SB(0, 1), b2 + hstep, voffB); PG8_STAGE(PG8_SA(0, 0), a2, voffA);
;             PG8_WAIT_V(8); PG8_WAIT_L(0); PG8_BAR; PG8_MMA(1, 0, At, B0); PG8_MMA(1, 1, At, B1); PG8_BAR; PG8_SCHED;
;             PG8_LDB(B0, 1, 0); PG8_LDB(B1, 1, 1); PG8_SCHED; PG8_LDA(At, 1, 0); PG8_STAGE(PG8_SA(0, 1), a2 + hstep, voffA);
;             PG8_WAIT_V(8); PG8_WAIT_L(0); PG8_BAR; PG8_MMA(0, 0, At, B0); PG8_MMA(0, 1, At, B1); PG8_BAR; PG8_SCHED;
;             PG8_LDA(At, 1, 1); PG8_STAGE(PG8_SB(1, 0), b3, voffB); PG8_STAGE(PG8_SB(1, 1), b3 + hstep, voffB); PG8_STAGE(PG8_SA(1, 0), a3, voffA);
;     __device__ __forceinline__ void operator()(const f32x4 (&acc)[2][2][4][2], const pg8::Unit& u, int wr, int wc, int fr, int fq) const {
; #pragma unroll
;         for (int ai = 0; ai < 2; ++ai)
; #pragma unroll
;             for (int m = 0; m < 4; ++m) { const int row = u.pm * 256 + ai * 128 + wr * 64 + m * 16 + fr;
;                 const float rstd = __builtin_amdgcn_rsqf(rss[row] * (1.f / D) + EPS);
;                 f32x4 h0, h1;
; #pragma unroll
;                 for (int i = 0; i < 4; ++i) { const float g0 = acc[ai][0][m][0][i] * rstd, u0 = acc[ai][1][m][0][i] * rstd, g1 = acc[ai][0][m][1][i] * rstd, u1 = acc[ai][1][m][1][i] * rstd;
;                     h0[i] = g0 * fast_sigmoid(g0) * u0; h1[i] = g1 * fast_sigmoid(g1) * u1; }
;                 *(u32x4*)(HFF + (size_t)row * DFF + u.pn * 128 + wc * 32 + 8 * fq) = pack8(h0, h1); }
;     }
	v_fmamk_f32 v36, v234, 0x3a800000, v155
	v_rsq_f32_e32 v36, v36
	v_mov_b32_e32 v33, v20
	v_mov_b32_e32 v34, v24
	v_mov_b32_e32 v35, v16
	v_mov_b32_e32 v20, v29
	v_mov_b32_e32 v16, v25
	v_mov_b32_e32 v24, v30
	v_mov_b32_e32 v25, v22
	v_mov_b32_e32 v29, v18
	v_mov_b32_e32 v18, v27
	v_mov_b32_e32 v32, v28
	v_mov_b32_e32 v28, v26
	v_mov_b32_e32 v22, v31
	v_add_u32_e32 v26, 0xb0, v150
	v_pk_mul_f32 v[20:21], v[20:21], v[36:37] op_sel_hi:[1,0]
	v_pk_mul_f32 v[16:17], v[16:17], v[36:37] op_sel_hi:[1,0]
	v_pk_mul_f32 v[24:25], v[24:25], v[36:37] op_sel_hi:[1,0]
	v_pk_mul_f32 v[18:19], v[18:19], v[36:37] op_sel_hi:[1,0]
	v_ashrrev_i32_e32 v27, 31, v26
	v_pk_mul_f32 v[32:33], v[32:33], v[36:37] op_sel_hi:[1,0]
	v_pk_mul_f32 v[34:35], v[34:35], v[36:37] op_sel_hi:[1,0]
	v_pk_mul_f32 v[28:29], v[28:29], v[36:37] op_sel_hi:[1,0]
	v_pk_mul_f32 v[22:23], v[22:23], v[36:37] op_sel_hi:[1,0]
	v_mul_f32_e32 v37, 0xbfb8aa3b, v21
	v_mul_f32_e32 v40, 0xbfb8aa3b, v17
	v_mul_f32_e32 v41, 0xbfb8aa3b, v25
	v_mul_f32_e32 v44, 0xbfb8aa3b, v19
	v_mad_i64_i32 v[30:31], s[24:25], v42, s49, v[120:121]
	v_lshl_add_u64 v[38:39], v[26:27], 2, s[6:7]
	v_mul_f32_e32 v27, 0xbfb8aa3b, v33
	v_mul_f32_e32 v36, 0xbfb8aa3b, v35
	v_mul_f32_e32 v42, 0xbfb8aa3b, v29
	v_mul_f32_e32 v43, 0xbfb8aa3b, v23
	v_exp_f32_e32 v37, v37
	v_exp_f32_e32 v40, v40
	v_exp_f32_e32 v41, v41
	v_exp_f32_e32 v44, v44
	v_exp_f32_e32 v27, v27
	v_exp_f32_e32 v36, v36
	v_exp_f32_e32 v42, v42
	v_exp_f32_e32 v43, v43
	v_add_f32_e32 v37, 1.0, v37
	v_add_f32_e32 v40, 1.0, v40
	v_add_f32_e32 v41, 1.0, v41
	v_add_f32_e32 v44, 1.0, v44
	v_add_f32_e32 v27, 1.0, v27
	v_add_f32_e32 v36, 1.0, v36
	v_add_f32_e32 v42, 1.0, v42
	v_add_f32_e32 v43, 1.0, v43
	v_rcp_f32_e32 v37, v37
	v_rcp_f32_e32 v40, v40
	v_rcp_f32_e32 v41, v41
	v_rcp_f32_e32 v44, v44
	v_rcp_f32_e32 v27, v27
	v_rcp_f32_e32 v36, v36
	v_rcp_f32_e32 v42, v42
	v_rcp_f32_e32 v43, v43
	v_lshl_add_u64 v[30:31], v[30:31], 0, s[22:23]
	v_lshl_add_u64 v[30:31], v[30:31], 0, s[0:1]
	v_mul_f32_e32 v21, v21, v37
	v_mul_f32_e32 v17, v17, v40
	v_mul_f32_e32 v25, v25, v41
	v_mul_f32_e32 v19, v19, v44
	v_lshl_add_u64 v[30:31], v[30:31], 0, v[140:141]
	v_mul_f32_e32 v27, v33, v27
	v_mul_f32_e32 v33, v35, v36
	v_mul_f32_e32 v29, v29, v42
	v_mul_f32_e32 v23, v23, v43
	v_mul_f32_e32 v20, v20, v21
	v_mul_f32_e32 v21, v16, v17
	v_mul_f32_e32 v17, v24, v25
	v_mul_f32_e32 v19, v18, v19
	v_mul_f32_e32 v27, v32, v27
	v_mul_f32_e32 v32, v34, v33
	v_mul_f32_e32 v24, v28, v29
	v_mul_f32_e32 v22, v22, v23
	v_cvt_pk_bf16_f32 v16, v27, v20
	v_cvt_pk_bf16_f32 v17, v17, v22
	v_cvt_pk_bf16_f32 v18, v32, v21
	v_cvt_pk_bf16_f32 v19, v24, v19
	global_store_dwordx4 v[30:31], v[16:19], off
	s_nop 0
	s_nop 0
	v_mov_b32_e32 v18, v8
	v_mov_b32_e32 v8, v14
	v_mov_b32_e32 v17, v4
	v_mov_b32_e32 v19, v0
	v_mov_b32_e32 v4, v13
	v_mov_b32_e32 v0, v9
	v_mov_b32_e32 v9, v6
	v_mov_b32_e32 v13, v2
	v_mov_b32_e32 v2, v11
	v_mov_b32_e32 v16, v12
	v_mov_b32_e32 v12, v10
	v_mov_b32_e32 v6, v15
	v_mad_i64_i32 v[10:11], s[24:25], v26, s49, v[120:121]
	v_lshl_add_u64 v[10:11], v[10:11], 0, s[22:23]
	v_lshl_add_u64 v[10:11], v[10:11], 0, s[0:1]
	v_lshl_add_u64 v[10:11], v[10:11], 0, v[140:141]
	s_waitcnt vmcnt(7)
	v_fmamk_f32 v14, v235, 0x3a800000, v155
	v_rsq_f32_e32 v14, v14
	s_nop 0
	v_pk_mul_f32 v[4:5], v[4:5], v[14:15] op_sel_hi:[1,0]
	v_pk_mul_f32 v[0:1], v[0:1], v[14:15] op_sel_hi:[1,0]
	v_pk_mul_f32 v[8:9], v[8:9], v[14:15] op_sel_hi:[1,0]
	v_pk_mul_f32 v[2:3], v[2:3], v[14:15] op_sel_hi:[1,0]
	v_pk_mul_f32 v[16:17], v[16:17], v[14:15] op_sel_hi:[1,0]
	v_pk_mul_f32 v[18:19], v[18:19], v[14:15] op_sel_hi:[1,0]
	v_pk_mul_f32 v[12:13], v[12:13], v[14:15] op_sel_hi:[1,0]
	v_pk_mul_f32 v[6:7], v[6:7], v[14:15] op_sel_hi:[1,0]
	v_mul_f32_e32 v20, 0xbfb8aa3b, v5
	v_mul_f32_e32 v21, 0xbfb8aa3b, v1
	v_mul_f32_e32 v22, 0xbfb8aa3b, v9
	v_mul_f32_e32 v25, 0xbfb8aa3b, v3
	v_mul_f32_e32 v14, 0xbfb8aa3b, v17
	v_mul_f32_e32 v15, 0xbfb8aa3b, v19
	v_mul_f32_e32 v23, 0xbfb8aa3b, v13
	v_mul_f32_e32 v24, 0xbfb8aa3b, v7
	v_exp_f32_e32 v20, v20
	v_exp_f32_e32 v21, v21
	v_exp_f32_e32 v22, v22
	v_exp_f32_e32 v25, v25
	v_exp_f32_e32 v14, v14
	v_exp_f32_e32 v15, v15
	v_exp_f32_e32 v23, v23
	v_exp_f32_e32 v24, v24
	v_add_f32_e32 v20, 1.0, v20
	v_add_f32_e32 v21, 1.0, v21
	v_add_f32_e32 v22, 1.0, v22
	v_add_f32_e32 v25, 1.0, v25
	v_add_f32_e32 v14, 1.0, v14
	v_add_f32_e32 v15, 1.0, v15
	v_add_f32_e32 v23, 1.0, v23
	v_add_f32_e32 v24, 1.0, v24
	v_rcp_f32_e32 v20, v20
	v_rcp_f32_e32 v21, v21
	v_rcp_f32_e32 v22, v22
	v_rcp_f32_e32 v25, v25
	v_rcp_f32_e32 v14, v14
	v_rcp_f32_e32 v15, v15
	v_rcp_f32_e32 v23, v23
	v_rcp_f32_e32 v24, v24
	v_mul_f32_e32 v5, v5, v20
	v_mul_f32_e32 v1, v1, v21
	v_mul_f32_e32 v9, v9, v22
	v_mul_f32_e32 v3, v3, v25
	v_mul_f32_e32 v14, v17, v14
	v_mul_f32_e32 v15, v19, v15
	v_mul_f32_e32 v13, v13, v23
	v_mul_f32_e32 v7, v7, v24
	v_mul_f32_e32 v4, v4, v5
	v_mul_f32_e32 v5, v0, v1
	v_mul_f32_e32 v1, v8, v9
	v_mul_f32_e32 v3, v2, v3
	v_mul_f32_e32 v14, v16, v14
	v_mul_f32_e32 v15, v18, v15
	v_mul_f32_e32 v8, v12, v13
	v_mul_f32_e32 v6, v6, v7
	v_cvt_pk_bf16_f32 v0, v14, v4
	v_cvt_pk_bf16_f32 v1, v1, v6
	v_cvt_pk_bf16_f32 v2, v15, v5
	v_cvt_pk_bf16_f32 v3, v8, v3
	global_store_dwordx4 v[10:11], v[0:3], off
	s_cbranch_vccnz .LBB0_852
	s_andn2_b64 vcc, exec, s[4:5]
	s_cbranch_vccnz .LBB0_851
	s_barrier
	s_branch .LBB0_851

; __device__ __forceinline__ u32x4 pack8(f32x4 a, f32x4 b) { u32x4 w; w.x = cvt_pk_bf16(a[0], a[1]); w.y = cvt_pk_bf16(a[2], a[3]); w.z = cvt_pk_bf16(b[0], b[1]); w.w = cvt_pk_bf16(b[2], b[3]); return w; }
;     __device__ __forceinline__ void operator()(const f32x4 (&acc)[2][2][4][2], const pg8::Unit& u, int wr, int wc, int fr, int fq) const {
; #pragma unroll
;         for (int ai = 0; ai < 2; ++ai)
; #pragma unroll
;             for (int m = 0; m < 4; ++m) { const int row = u.pm * 256 + ai * 128 + wr * 64 + m * 16 + fr; float ss = 0.f;
; #pragma unroll
;                 for (int bj = 0; bj < 2; ++bj) { const int col = u.pn * 256 + bj * 128 + wc * 32 + 8 * fq;
;                     f32x4 x0, x1; unpack_bf16x8(*(const u32x4*)(X2B + (size_t)row * D + col), x0, x1);
;                     const f32x4 v0 = acc[ai][bj][m][0] + x0, v1 = acc[ai][bj][m][1] + x1;
;                     ss += (v0[0] * v0[0] + v0[1] * v0[1]) + (v0[2] * v0[2] + v0[3] * v0[3]) + (v1[0] * v1[0] + v1[1] * v1[1]) + (v1[2] * v1[2] + v1[3] * v1[3]);
;                     *(u32x4*)(X3B + (size_t)row * D + col) = pack8(v0, v1); }
;                 ss += __shfl_xor(ss, 16); ss += __shfl_xor(ss, 32);
;                 if (fq == 0) atomicAdd(rss + row, ss); }
;     }
.LBB0_934:
	v_lshl_add_u32 v148, s48, 4, v133
	v_lshl_or_b32 v146, s47, 8, v151
	v_ashrrev_i32_e32 v149, 31, v148
	v_lshlrev_b64 v[160:161], 11, v[148:149]
	v_ashrrev_i32_e32 v147, 31, v146
	v_lshl_add_u64 v[156:157], s[8:9], 0, v[160:161]
	v_lshlrev_b64 v[146:147], 1, v[146:147]
	v_lshl_add_u64 v[162:163], v[156:157], 0, v[146:147]
	v_mov_b64_e32 v[242:243], v[162:163]
	s_mov_b64 s[96:97], 0x8000
	s_mov_b64 s[98:99], 0x28000
	global_load_dwordx4 v[170:173], v[242:243], off
	global_load_dwordx4 v[174:177], v[242:243], off offset:256
	v_lshl_add_u64 v[242:243], v[242:243], 0, s[96:97]
	global_load_dwordx4 v[178:181], v[242:243], off
	global_load_dwordx4 v[182:185], v[242:243], off offset:256
	v_lshl_add_u64 v[242:243], v[242:243], 0, s[96:97]
	global_load_dwordx4 v[186:189], v[242:243], off
	global_load_dwordx4 v[190:193], v[242:243], off offset:256
	v_lshl_add_u64 v[242:243], v[242:243], 0, s[96:97]
	global_load_dwordx4 v[194:197], v[242:243], off
	global_load_dwordx4 v[198:201], v[242:243], off offset:256
	v_lshl_add_u64 v[242:243], v[242:243], 0, s[98:99]
	global_load_dwordx4 v[202:205], v[242:243], off
	global_load_dwordx4 v[206:209], v[242:243], off offset:256
	v_lshl_add_u64 v[242:243], v[242:243], 0, s[96:97]
	global_load_dwordx4 v[210:213], v[242:243], off
	global_load_dwordx4 v[214:217], v[242:243], off offset:256
	v_lshl_add_u64 v[242:243], v[242:243], 0, s[96:97]
	global_load_dwordx4 v[218:221], v[242:243], off
	global_load_dwordx4 v[222:225], v[242:243], off offset:256
	v_lshl_add_u64 v[242:243], v[242:243], 0, s[96:97]
	global_load_dwordx4 v[234:237], v[242:243], off
	global_load_dwordx4 v[238:241], v[242:243], off offset:256
	s_waitcnt vmcnt(15)
	v_lshlrev_b32_e32 v164, 16, v170
	v_and_b32_e32 v165, 0xffff0000, v170
	v_lshlrev_b32_e32 v156, 16, v171
	v_and_b32_e32 v157, 0xffff0000, v171
	v_lshlrev_b32_e32 v166, 16, v172
	v_and_b32_e32 v167, 0xffff0000, v172
	v_lshlrev_b32_e32 v158, 16, v173
	v_and_b32_e32 v159, 0xffff0000, v173
	v_pk_add_f32 v[126:127], v[126:127], v[156:157]
	v_pk_add_f32 v[164:165], v[124:125], v[164:165]
	v_pk_add_f32 v[168:169], v[122:123], v[158:159]
	v_pk_add_f32 v[166:167], v[120:121], v[166:167]
	v_cvt_pk_bf16_f32 v122, v164, v165
	v_cvt_pk_bf16_f32 v123, v126, v127
	v_and_b32_e32 v121, 64, v155
	v_cvt_pk_bf16_f32 v124, v166, v167
	v_cvt_pk_bf16_f32 v125, v168, v169
	s_nop 0
	v_xor_b32_e32 v120, 16, v155
	v_add_u32_e32 v121, 64, v121
	v_xor_b32_e32 v162, 32, v155
	v_cmp_lt_i32_e32 vcc, v120, v121
	v_mul_f32_e32 v127, v127, v127
	v_mul_f32_e32 v163, v167, v167
	v_cndmask_b32_e32 v120, v155, v120, vcc
	v_cmp_lt_i32_e32 vcc, v162, v121
	v_fmac_f32_e32 v127, v126, v126
	v_fmac_f32_e32 v163, v166, v166
	v_cndmask_b32_e32 v121, v155, v162, vcc
	v_mul_f32_e32 v162, v165, v165
	v_fmac_f32_e32 v162, v164, v164
	v_mul_f32_e32 v165, v169, v169
	v_add_f32_e32 v126, v162, v127
	v_fmac_f32_e32 v165, v168, v168
	v_add_f32_e32 v126, v163, v126
	v_add_f32_e32 v164, v165, v126
	v_lshlrev_b32_e32 v120, 2, v120
	s_waitcnt vmcnt(14)
	v_lshlrev_b32_e32 v126, 16, v174
	v_and_b32_e32 v127, 0xffff0000, v174
	v_lshlrev_b32_e32 v156, 16, v175
	v_and_b32_e32 v157, 0xffff0000, v175
	v_lshlrev_b32_e32 v162, 16, v176
	v_and_b32_e32 v163, 0xffff0000, v176
	v_pk_add_f32 v[118:119], v[118:119], v[156:157]
	v_pk_add_f32 v[116:117], v[116:117], v[126:127]
	v_lshlrev_b32_e32 v158, 16, v177
	v_and_b32_e32 v159, 0xffff0000, v177
	v_pk_add_f32 v[156:157], v[112:113], v[162:163]
	v_mul_f32_e32 v112, v117, v117
	v_mul_f32_e32 v113, v119, v119
	v_pk_add_f32 v[126:127], v[114:115], v[158:159]
	v_mul_f32_e32 v114, v157, v157
	v_fmac_f32_e32 v112, v116, v116
	v_fmac_f32_e32 v113, v118, v118
	v_mul_f32_e32 v115, v127, v127
	v_fmac_f32_e32 v114, v156, v156
	v_add_f32_e32 v112, v112, v113
	v_fmac_f32_e32 v115, v126, v126
	v_add_f32_e32 v112, v114, v112
	v_add_f32_e32 v112, v115, v112
	v_add_f32_e32 v114, v164, v112
	ds_bpermute_b32 v115, v120, v114
	v_lshl_add_u64 v[112:113], s[10:11], 0, v[160:161]
	v_lshl_add_u64 v[158:159], v[112:113], 0, v[146:147]
	global_store_dwordx4 v[158:159], v[122:125], off
	v_cvt_pk_bf16_f32 v116, v116, v117
	s_waitcnt lgkmcnt(0)
	v_add_f32_e32 v112, v114, v115
	v_lshlrev_b32_e32 v114, 2, v121
	ds_bpermute_b32 v113, v114, v112
	v_cvt_pk_bf16_f32 v117, v118, v119
	v_cvt_pk_bf16_f32 v118, v156, v157
	v_cvt_pk_bf16_f32 v119, v126, v127
	global_store_dwordx4 v[158:159], v[116:119], off offset:256
	s_and_saveexec_b64 s[20:21], s[2:3]
	s_cbranch_execz .LBB0_936
	v_lshl_add_u64 v[116:117], v[148:149], 2, s[12:13]
	s_waitcnt lgkmcnt(0)
	v_add_f32_e32 v112, v112, v113
	global_atomic_add_f32 v[116:117], v112, off
; __device__ __forceinline__ u32x4 pack8(f32x4 a, f32x4 b) { u32x4 w; w.x = cvt_pk_bf16(a[0], a[1]); w.y = cvt_pk_bf16(a[2], a[3]); w.z = cvt_pk_bf16(b[0], b[1]); w.w = cvt_pk_bf16(b[2], b[3]); return w; }
;     __device__ __forceinline__ void operator()(const f32x4 (&acc)[2][2][4][2], const pg8::Unit& u, int wr, int wc, int fr, int fq) const {
; #pragma unroll
;         for (int ai = 0; ai < 2; ++ai)
; #pragma unroll
;             for (int m = 0; m < 4; ++m) { const int row = u.pm * 256 + ai * 128 + wr * 64 + m * 16 + fr; float ss = 0.f;
; #pragma unroll
;                 for (int bj = 0; bj < 2; ++bj) { const int col = u.pn * 256 + bj * 128 + wc * 32 + 8 * fq;
;                     f32x4 x0, x1; unpack_bf16x8(*(const u32x4*)(X2B + (size_t)row * D + col), x0, x1);
;                     const f32x4 v0 = acc[ai][bj][m][0] + x0, v1 = acc[ai][bj][m][1] + x1;
;                     ss += (v0[0] * v0[0] + v0[1] * v0[1]) + (v0[2] * v0[2] + v0[3] * v0[3]) + (v1[0] * v1[0] + v1[1] * v1[1]) + (v1[2] * v1[2] + v1[3] * v1[3]);
;                     *(u32x4*)(X3B + (size_t)row * D + col) = pack8(v0, v1); }
;                 ss += __shfl_xor(ss, 16); ss += __shfl_xor(ss, 32);
;                 if (fq == 0) atomicAdd(rss + row, ss); }
;     }
.LBB0_936:
	s_or_b64 exec, exec, s[20:21]
	v_add_u32_e32 v112, 16, v148
	s_waitcnt lgkmcnt(0)
	v_ashrrev_i32_e32 v113, 31, v112
	v_lshlrev_b64 v[122:123], 11, v[112:113]
	v_lshl_add_u64 v[116:117], s[8:9], 0, v[122:123]
	v_lshl_add_u64 v[124:125], v[116:117], 0, v[146:147]
	s_nop 0
	s_waitcnt vmcnt(15)
	v_lshlrev_b32_e32 v126, 16, v178
	v_and_b32_e32 v127, 0xffff0000, v178
	v_lshlrev_b32_e32 v116, 16, v179
	v_and_b32_e32 v117, 0xffff0000, v179
	v_lshlrev_b32_e32 v156, 16, v180
	v_and_b32_e32 v157, 0xffff0000, v180
	v_lshlrev_b32_e32 v118, 16, v181
	v_and_b32_e32 v119, 0xffff0000, v181
	v_pk_add_f32 v[116:117], v[110:111], v[116:117]
	v_pk_add_f32 v[126:127], v[108:109], v[126:127]
	v_pk_add_f32 v[118:119], v[106:107], v[118:119]
	v_pk_add_f32 v[156:157], v[104:105], v[156:157]
	v_cvt_pk_bf16_f32 v104, v126, v127
	v_cvt_pk_bf16_f32 v105, v116, v117
	v_mul_f32_e32 v115, v127, v127
	v_cvt_pk_bf16_f32 v106, v156, v157
	v_cvt_pk_bf16_f32 v107, v118, v119
	s_nop 0
	v_mul_f32_e32 v117, v117, v117
	v_mul_f32_e32 v121, v157, v157
	v_fmac_f32_e32 v115, v126, v126
	v_fmac_f32_e32 v117, v116, v116
	v_mul_f32_e32 v119, v119, v119
	v_fmac_f32_e32 v121, v156, v156
	v_add_f32_e32 v115, v115, v117
	v_fmac_f32_e32 v119, v118, v118
	v_add_f32_e32 v115, v121, v115
	v_add_f32_e32 v115, v119, v115
	s_waitcnt vmcnt(14)
	v_lshlrev_b32_e32 v116, 16, v182
	v_and_b32_e32 v117, 0xffff0000, v182
	v_lshlrev_b32_e32 v108, 16, v183
	v_and_b32_e32 v109, 0xffff0000, v183
	v_lshlrev_b32_e32 v118, 16, v184
	v_and_b32_e32 v119, 0xffff0000, v184
	v_lshlrev_b32_e32 v110, 16, v185
	v_and_b32_e32 v111, 0xffff0000, v185
	v_pk_add_f32 v[102:103], v[102:103], v[108:109]
	v_pk_add_f32 v[100:101], v[100:101], v[116:117]
	v_pk_add_f32 v[108:109], v[98:99], v[110:111]
	v_pk_add_f32 v[110:111], v[96:97], v[118:119]
	v_mul_f32_e32 v96, v101, v101
	v_mul_f32_e32 v97, v103, v103
	v_mul_f32_e32 v98, v111, v111
	v_fmac_f32_e32 v96, v100, v100
	v_fmac_f32_e32 v97, v102, v102
	v_mul_f32_e32 v99, v109, v109
	v_fmac_f32_e32 v98, v110, v110
	v_add_f32_e32 v96, v96, v97
	v_add_f32_e32 v96, v98, v96
	v_fmac_f32_e32 v99, v108, v108
	v_add_f32_e32 v96, v99, v96
	v_add_f32_e32 v99, v115, v96
	ds_bpermute_b32 v115, v120, v99
	v_lshl_add_u64 v[96:97], s[10:11], 0, v[122:123]
	v_lshl_add_u64 v[116:117], v[96:97], 0, v[146:147]
	global_store_dwordx4 v[116:117], v[104:107], off
	v_cvt_pk_bf16_f32 v98, v100, v101
	s_waitcnt lgkmcnt(0)
	v_add_f32_e32 v96, v99, v115
	ds_bpermute_b32 v97, v114, v96
	v_cvt_pk_bf16_f32 v99, v102, v103
	v_cvt_pk_bf16_f32 v100, v110, v111
	v_cvt_pk_bf16_f32 v101, v108, v109
	global_store_dwordx4 v[116:117], v[98:101], off offset:256
	s_and_saveexec_b64 s[20:21], s[2:3]
	s_cbranch_execz .LBB0_938
	v_lshl_add_u64 v[98:99], v[112:113], 2, s[12:13]
	s_waitcnt lgkmcnt(0)
	v_add_f32_e32 v96, v96, v97
	global_atomic_add_f32 v[98:99], v96, off
.LBB0_938:
	s_or_b64 exec, exec, s[20:21]
	v_add_u32_e32 v96, 32, v148
	s_waitcnt lgkmcnt(0)
	v_ashrrev_i32_e32 v97, 31, v96
	v_lshlrev_b64 v[102:103], 11, v[96:97]
	v_lshl_add_u64 v[98:99], s[8:9], 0, v[102:103]
	v_lshl_add_u64 v[104:105], v[98:99], 0, v[146:147]
	s_nop 0
	s_waitcnt vmcnt(15)
	v_lshlrev_b32_e32 v106, 16, v186
	v_and_b32_e32 v107, 0xffff0000, v186
	v_lshlrev_b32_e32 v98, 16, v187
	v_and_b32_e32 v99, 0xffff0000, v187
	v_lshlrev_b32_e32 v108, 16, v188
	v_and_b32_e32 v109, 0xffff0000, v188
	v_lshlrev_b32_e32 v100, 16, v189
	v_and_b32_e32 v101, 0xffff0000, v189
	v_pk_add_f32 v[98:99], v[94:95], v[98:99]
	v_pk_add_f32 v[106:107], v[92:93], v[106:107]
	v_pk_add_f32 v[100:101], v[90:91], v[100:101]
	v_pk_add_f32 v[108:109], v[88:89], v[108:109]
	v_cvt_pk_bf16_f32 v88, v106, v107
	v_cvt_pk_bf16_f32 v89, v98, v99
	v_mul_f32_e32 v99, v99, v99
	v_cvt_pk_bf16_f32 v90, v108, v109
	v_cvt_pk_bf16_f32 v91, v100, v101
	s_nop 0
	v_mul_f32_e32 v104, v107, v107
	v_mul_f32_e32 v105, v109, v109
	v_fmac_f32_e32 v104, v106, v106
	v_fmac_f32_e32 v99, v98, v98
	v_mul_f32_e32 v101, v101, v101
	v_fmac_f32_e32 v105, v108, v108
	v_add_f32_e32 v98, v104, v99
	v_fmac_f32_e32 v101, v100, v100
	v_add_f32_e32 v98, v105, v98
	v_add_f32_e32 v104, v101, v98
	s_waitcnt vmcnt(14)
	v_lshlrev_b32_e32 v98, 16, v190
	v_and_b32_e32 v99, 0xffff0000, v190
	v_lshlrev_b32_e32 v92, 16, v191
	v_and_b32_e32 v93, 0xffff0000, v191
	v_lshlrev_b32_e32 v100, 16, v192
	v_and_b32_e32 v101, 0xffff0000, v192
	v_lshlrev_b32_e32 v94, 16, v193
	v_and_b32_e32 v95, 0xffff0000, v193
	v_pk_add_f32 v[86:87], v[86:87], v[92:93]
	v_pk_add_f32 v[84:85], v[84:85], v[98:99]
	v_pk_add_f32 v[92:93], v[82:83], v[94:95]
	v_pk_add_f32 v[94:95], v[80:81], v[100:101]
	v_mul_f32_e32 v80, v85, v85
	v_mul_f32_e32 v81, v87, v87
	v_mul_f32_e32 v82, v95, v95
	v_fmac_f32_e32 v80, v84, v84
	v_fmac_f32_e32 v81, v86, v86
	v_mul_f32_e32 v83, v93, v93
	v_fmac_f32_e32 v82, v94, v94
	v_add_f32_e32 v80, v80, v81
	v_add_f32_e32 v80, v82, v80
	v_fmac_f32_e32 v83, v92, v92
	v_add_f32_e32 v80, v83, v80
	v_add_f32_e32 v83, v104, v80
	ds_bpermute_b32 v100, v120, v83
	v_lshl_add_u64 v[80:81], s[10:11], 0, v[102:103]
	v_lshl_add_u64 v[98:99], v[80:81], 0, v[146:147]
	global_store_dwordx4 v[98:99], v[88:91], off
	v_cvt_pk_bf16_f32 v82, v84, v85
	s_waitcnt lgkmcnt(0)
	v_add_f32_e32 v80, v83, v100
	ds_bpermute_b32 v81, v114, v80
	v_cvt_pk_bf16_f32 v83, v86, v87
	v_cvt_pk_bf16_f32 v84, v94, v95
	v_cvt_pk_bf16_f32 v85, v92, v93
	global_store_dwordx4 v[98:99], v[82:85], off offset:256
	s_and_saveexec_b64 s[20:21], s[2:3]
	s_cbranch_execz .LBB0_940
	v_lshl_add_u64 v[82:83], v[96:97], 2, s[12:13]
	s_waitcnt lgkmcnt(0)
	v_add_f32_e32 v80, v80, v81
	global_atomic_add_f32 v[82:83], v80, off
; __device__ __forceinline__ u32x4 pack8(f32x4 a, f32x4 b) { u32x4 w; w.x = cvt_pk_bf16(a[0], a[1]); w.y = cvt_pk_bf16(a[2], a[3]); w.z = cvt_pk_bf16(b[0], b[1]); w.w = cvt_pk_bf16(b[2], b[3]); return w; }
;     __device__ __forceinline__ void operator()(const f32x4 (&acc)[2][2][4][2], const pg8::Unit& u, int wr, int wc, int fr, int fq) const {
; #pragma unroll
;         for (int ai = 0; ai < 2; ++ai)
; #pragma unroll
;             for (int m = 0; m < 4; ++m) { const int row = u.pm * 256 + ai * 128 + wr * 64 + m * 16 + fr; float ss = 0.f;
; #pragma unroll
;                 for (int bj = 0; bj < 2; ++bj) { const int col = u.pn * 256 + bj * 128 + wc * 32 + 8 * fq;
;                     f32x4 x0, x1; unpack_bf16x8(*(const u32x4*)(X2B + (size_t)row * D + col), x0, x1);
;                     const f32x4 v0 = acc[ai][bj][m][0] + x0, v1 = acc[ai][bj][m][1] + x1;
;                     ss += (v0[0] * v0[0] + v0[1] * v0[1]) + (v0[2] * v0[2] + v0[3] * v0[3]) + (v1[0] * v1[0] + v1[1] * v1[1]) + (v1[2] * v1[2] + v1[3] * v1[3]);
;                     *(u32x4*)(X3B + (size_t)row * D + col) = pack8(v0, v1); }
;                 ss += __shfl_xor(ss, 16); ss += __shfl_xor(ss, 32);
;                 if (fq == 0) atomicAdd(rss + row, ss); }
;     }
.LBB0_940:
	s_or_b64 exec, exec, s[20:21]
	v_add_u32_e32 v80, 48, v148
	s_waitcnt lgkmcnt(0)
	v_ashrrev_i32_e32 v81, 31, v80
	v_lshlrev_b64 v[86:87], 11, v[80:81]
	v_lshl_add_u64 v[82:83], s[8:9], 0, v[86:87]
	v_lshl_add_u64 v[88:89], v[82:83], 0, v[146:147]
	s_nop 0
	s_waitcnt vmcnt(15)
	v_lshlrev_b32_e32 v90, 16, v194
	v_and_b32_e32 v91, 0xffff0000, v194
	v_lshlrev_b32_e32 v82, 16, v195
	v_and_b32_e32 v83, 0xffff0000, v195
	v_lshlrev_b32_e32 v92, 16, v196
	v_and_b32_e32 v93, 0xffff0000, v196
	v_lshlrev_b32_e32 v84, 16, v197
	v_and_b32_e32 v85, 0xffff0000, v197
	v_pk_add_f32 v[82:83], v[78:79], v[82:83]
	v_pk_add_f32 v[90:91], v[76:77], v[90:91]
	v_pk_add_f32 v[84:85], v[74:75], v[84:85]
	v_pk_add_f32 v[92:93], v[72:73], v[92:93]
	v_cvt_pk_bf16_f32 v72, v90, v91
	v_cvt_pk_bf16_f32 v73, v82, v83
	v_mul_f32_e32 v83, v83, v83
	v_cvt_pk_bf16_f32 v74, v92, v93
	v_cvt_pk_bf16_f32 v75, v84, v85
	s_nop 0
	v_mul_f32_e32 v88, v91, v91
	v_mul_f32_e32 v89, v93, v93
	v_fmac_f32_e32 v88, v90, v90
	v_fmac_f32_e32 v83, v82, v82
	v_mul_f32_e32 v85, v85, v85
	v_fmac_f32_e32 v89, v92, v92
	v_add_f32_e32 v82, v88, v83
	v_fmac_f32_e32 v85, v84, v84
	v_add_f32_e32 v82, v89, v82
	v_add_f32_e32 v88, v85, v82
	s_waitcnt vmcnt(14)
	v_lshlrev_b32_e32 v82, 16, v198
	v_and_b32_e32 v83, 0xffff0000, v198
	v_lshlrev_b32_e32 v76, 16, v199
	v_and_b32_e32 v77, 0xffff0000, v199
	v_lshlrev_b32_e32 v84, 16, v200
	v_and_b32_e32 v85, 0xffff0000, v200
	v_lshlrev_b32_e32 v78, 16, v201
	v_and_b32_e32 v79, 0xffff0000, v201
	v_pk_add_f32 v[70:71], v[70:71], v[76:77]
	v_pk_add_f32 v[68:69], v[68:69], v[82:83]
	v_pk_add_f32 v[76:77], v[66:67], v[78:79]
	v_pk_add_f32 v[78:79], v[64:65], v[84:85]
	v_mul_f32_e32 v64, v69, v69
	v_mul_f32_e32 v65, v71, v71
	v_mul_f32_e32 v66, v79, v79
	v_fmac_f32_e32 v64, v68, v68
	v_fmac_f32_e32 v65, v70, v70
	v_mul_f32_e32 v67, v77, v77
	v_fmac_f32_e32 v66, v78, v78
	v_add_f32_e32 v64, v64, v65
	v_add_f32_e32 v64, v66, v64
	v_fmac_f32_e32 v67, v76, v76
	v_add_f32_e32 v64, v67, v64
	v_add_f32_e32 v67, v88, v64
	ds_bpermute_b32 v84, v120, v67
	v_lshl_add_u64 v[64:65], s[10:11], 0, v[86:87]
	v_lshl_add_u64 v[82:83], v[64:65], 0, v[146:147]
	global_store_dwordx4 v[82:83], v[72:75], off
	v_cvt_pk_bf16_f32 v66, v68, v69
	s_waitcnt lgkmcnt(0)
	v_add_f32_e32 v64, v67, v84
	ds_bpermute_b32 v65, v114, v64
	v_cvt_pk_bf16_f32 v67, v70, v71
	v_cvt_pk_bf16_f32 v68, v78, v79
	v_cvt_pk_bf16_f32 v69, v76, v77
	global_store_dwordx4 v[82:83], v[66:69], off offset:256
	s_and_saveexec_b64 s[20:21], s[2:3]
	s_cbranch_execz .LBB0_942
	v_lshl_add_u64 v[66:67], v[80:81], 2, s[12:13]
	s_waitcnt lgkmcnt(0)
	v_add_f32_e32 v64, v64, v65
	global_atomic_add_f32 v[66:67], v64, off
.LBB0_942:
	s_or_b64 exec, exec, s[20:21]
	v_add_u32_e32 v64, 0x80, v148
	s_waitcnt lgkmcnt(0)
	v_ashrrev_i32_e32 v65, 31, v64
	v_lshlrev_b64 v[70:71], 11, v[64:65]
	v_lshl_add_u64 v[66:67], s[8:9], 0, v[70:71]
	v_lshl_add_u64 v[72:73], v[66:67], 0, v[146:147]
	s_nop 0
	s_waitcnt vmcnt(15)
	v_lshlrev_b32_e32 v74, 16, v202
	v_and_b32_e32 v75, 0xffff0000, v202
	v_lshlrev_b32_e32 v66, 16, v203
	v_and_b32_e32 v67, 0xffff0000, v203
	v_lshlrev_b32_e32 v76, 16, v204
	v_and_b32_e32 v77, 0xffff0000, v204
	v_lshlrev_b32_e32 v68, 16, v205
	v_and_b32_e32 v69, 0xffff0000, v205
	v_pk_add_f32 v[66:67], v[62:63], v[66:67]
	v_pk_add_f32 v[74:75], v[60:61], v[74:75]
	v_pk_add_f32 v[68:69], v[58:59], v[68:69]
	v_pk_add_f32 v[76:77], v[56:57], v[76:77]
	v_cvt_pk_bf16_f32 v56, v74, v75
	v_cvt_pk_bf16_f32 v57, v66, v67
	v_mul_f32_e32 v67, v67, v67
	v_cvt_pk_bf16_f32 v58, v76, v77
	v_cvt_pk_bf16_f32 v59, v68, v69
	s_nop 0
	v_mul_f32_e32 v72, v75, v75
	v_mul_f32_e32 v73, v77, v77
	v_fmac_f32_e32 v72, v74, v74
	v_fmac_f32_e32 v67, v66, v66
	v_mul_f32_e32 v69, v69, v69
	v_fmac_f32_e32 v73, v76, v76
	v_add_f32_e32 v66, v72, v67
	v_fmac_f32_e32 v69, v68, v68
	v_add_f32_e32 v66, v73, v66
	v_add_f32_e32 v72, v69, v66
	s_waitcnt vmcnt(14)
	v_lshlrev_b32_e32 v66, 16, v206
	v_and_b32_e32 v67, 0xffff0000, v206
	v_lshlrev_b32_e32 v60, 16, v207
	v_and_b32_e32 v61, 0xffff0000, v207
	v_lshlrev_b32_e32 v68, 16, v208
	v_and_b32_e32 v69, 0xffff0000, v208
	v_lshlrev_b32_e32 v62, 16, v209
	v_and_b32_e32 v63, 0xffff0000, v209
	v_pk_add_f32 v[54:55], v[54:55], v[60:61]
	v_pk_add_f32 v[52:53], v[52:53], v[66:67]
	v_pk_add_f32 v[60:61], v[50:51], v[62:63]
	v_pk_add_f32 v[62:63], v[48:49], v[68:69]
	v_mul_f32_e32 v48, v53, v53
	v_mul_f32_e32 v49, v55, v55
	v_mul_f32_e32 v50, v63, v63
	v_fmac_f32_e32 v48, v52, v52
	v_fmac_f32_e32 v49, v54, v54
	v_mul_f32_e32 v51, v61, v61
	v_fmac_f32_e32 v50, v62, v62
	v_add_f32_e32 v48, v48, v49
	v_add_f32_e32 v48, v50, v48
	v_fmac_f32_e32 v51, v60, v60
	v_add_f32_e32 v48, v51, v48
	v_add_f32_e32 v51, v72, v48
	ds_bpermute_b32 v68, v120, v51
	v_lshl_add_u64 v[48:49], s[10:11], 0, v[70:71]
	v_lshl_add_u64 v[66:67], v[48:49], 0, v[146:147]
	global_store_dwordx4 v[66:67], v[56:59], off
	v_cvt_pk_bf16_f32 v50, v52, v53
	s_waitcnt lgkmcnt(0)
	v_add_f32_e32 v48, v51, v68
	ds_bpermute_b32 v49, v114, v48
	v_cvt_pk_bf16_f32 v51, v54, v55
	v_cvt_pk_bf16_f32 v52, v62, v63
	v_cvt_pk_bf16_f32 v53, v60, v61
	global_store_dwordx4 v[66:67], v[50:53], off offset:256
	s_and_saveexec_b64 s[20:21], s[2:3]
	s_cbranch_execz .LBB0_944
	v_lshl_add_u64 v[50:51], v[64:65], 2, s[12:13]
	s_waitcnt lgkmcnt(0)
	v_add_f32_e32 v48, v48, v49
	global_atomic_add_f32 v[50:51], v48, off
; __device__ __forceinline__ u32x4 pack8(f32x4 a, f32x4 b) { u32x4 w; w.x = cvt_pk_bf16(a[0], a[1]); w.y = cvt_pk_bf16(a[2], a[3]); w.z = cvt_pk_bf16(b[0], b[1]); w.w = cvt_pk_bf16(b[2], b[3]); return w; }
;     __device__ __forceinline__ void operator()(const f32x4 (&acc)[2][2][4][2], const pg8::Unit& u, int wr, int wc, int fr, int fq) const {
; #pragma unroll
;         for (int ai = 0; ai < 2; ++ai)
; #pragma unroll
;             for (int m = 0; m < 4; ++m) { const int row = u.pm * 256 + ai * 128 + wr * 64 + m * 16 + fr; float ss = 0.f;
; #pragma unroll
;                 for (int bj = 0; bj < 2; ++bj) { const int col = u.pn * 256 + bj * 128 + wc * 32 + 8 * fq;
;                     f32x4 x0, x1; unpack_bf16x8(*(const u32x4*)(X2B + (size_t)row * D + col), x0, x1);
;                     const f32x4 v0 = acc[ai][bj][m][0] + x0, v1 = acc[ai][bj][m][1] + x1;
;                     ss += (v0[0] * v0[0] + v0[1] * v0[1]) + (v0[2] * v0[2] + v0[3] * v0[3]) + (v1[0] * v1[0] + v1[1] * v1[1]) + (v1[2] * v1[2] + v1[3] * v1[3]);
;                     *(u32x4*)(X3B + (size_t)row * D + col) = pack8(v0, v1); }
;                 ss += __shfl_xor(ss, 16); ss += __shfl_xor(ss, 32);
;                 if (fq == 0) atomicAdd(rss + row, ss); }
;     }
.LBB0_944:
	s_or_b64 exec, exec, s[20:21]
	v_add_u32_e32 v48, 0x90, v148
	s_waitcnt lgkmcnt(0)
	v_ashrrev_i32_e32 v49, 31, v48
	v_lshlrev_b64 v[54:55], 11, v[48:49]
	v_lshl_add_u64 v[50:51], s[8:9], 0, v[54:55]
	v_lshl_add_u64 v[56:57], v[50:51], 0, v[146:147]
	s_nop 0
	s_waitcnt vmcnt(15)
	v_lshlrev_b32_e32 v58, 16, v210
	v_and_b32_e32 v59, 0xffff0000, v210
	v_lshlrev_b32_e32 v50, 16, v211
	v_and_b32_e32 v51, 0xffff0000, v211
	v_lshlrev_b32_e32 v60, 16, v212
	v_and_b32_e32 v61, 0xffff0000, v212
	v_lshlrev_b32_e32 v52, 16, v213
	v_and_b32_e32 v53, 0xffff0000, v213
	v_pk_add_f32 v[50:51], v[46:47], v[50:51]
	v_pk_add_f32 v[58:59], v[44:45], v[58:59]
	v_pk_add_f32 v[52:53], v[42:43], v[52:53]
	v_pk_add_f32 v[60:61], v[40:41], v[60:61]
	v_cvt_pk_bf16_f32 v40, v58, v59
	v_cvt_pk_bf16_f32 v41, v50, v51
	v_mul_f32_e32 v51, v51, v51
	v_cvt_pk_bf16_f32 v42, v60, v61
	v_cvt_pk_bf16_f32 v43, v52, v53
	s_nop 0
	v_mul_f32_e32 v56, v59, v59
	v_mul_f32_e32 v57, v61, v61
	v_fmac_f32_e32 v56, v58, v58
	v_fmac_f32_e32 v51, v50, v50
	v_mul_f32_e32 v53, v53, v53
	v_fmac_f32_e32 v57, v60, v60
	v_add_f32_e32 v50, v56, v51
	v_fmac_f32_e32 v53, v52, v52
	v_add_f32_e32 v50, v57, v50
	v_add_f32_e32 v56, v53, v50
	s_waitcnt vmcnt(14)
	v_lshlrev_b32_e32 v50, 16, v214
	v_and_b32_e32 v51, 0xffff0000, v214
	v_lshlrev_b32_e32 v44, 16, v215
	v_and_b32_e32 v45, 0xffff0000, v215
	v_lshlrev_b32_e32 v52, 16, v216
	v_and_b32_e32 v53, 0xffff0000, v216
	v_lshlrev_b32_e32 v46, 16, v217
	v_and_b32_e32 v47, 0xffff0000, v217
	v_pk_add_f32 v[38:39], v[38:39], v[44:45]
	v_pk_add_f32 v[36:37], v[36:37], v[50:51]
	v_pk_add_f32 v[44:45], v[34:35], v[46:47]
	v_pk_add_f32 v[46:47], v[32:33], v[52:53]
	v_mul_f32_e32 v32, v37, v37
	v_mul_f32_e32 v33, v39, v39
	v_mul_f32_e32 v34, v47, v47
	v_fmac_f32_e32 v32, v36, v36
	v_fmac_f32_e32 v33, v38, v38
	v_mul_f32_e32 v35, v45, v45
	v_fmac_f32_e32 v34, v46, v46
	v_add_f32_e32 v32, v32, v33
	v_add_f32_e32 v32, v34, v32
	v_fmac_f32_e32 v35, v44, v44
	v_add_f32_e32 v32, v35, v32
	v_add_f32_e32 v35, v56, v32
	ds_bpermute_b32 v52, v120, v35
	v_lshl_add_u64 v[32:33], s[10:11], 0, v[54:55]
	v_lshl_add_u64 v[50:51], v[32:33], 0, v[146:147]
	global_store_dwordx4 v[50:51], v[40:43], off
	v_cvt_pk_bf16_f32 v34, v36, v37
	s_waitcnt lgkmcnt(0)
	v_add_f32_e32 v32, v35, v52
	ds_bpermute_b32 v33, v114, v32
	v_cvt_pk_bf16_f32 v35, v38, v39
	v_cvt_pk_bf16_f32 v36, v46, v47
	v_cvt_pk_bf16_f32 v37, v44, v45
	global_store_dwordx4 v[50:51], v[34:37], off offset:256
	s_and_saveexec_b64 s[20:21], s[2:3]
	s_cbranch_execz .LBB0_946
	v_lshl_add_u64 v[34:35], v[48:49], 2, s[12:13]
	s_waitcnt lgkmcnt(0)
	v_add_f32_e32 v32, v32, v33
	global_atomic_add_f32 v[34:35], v32, off
; __device__ __forceinline__ u32x4 pack8(f32x4 a, f32x4 b) { u32x4 w; w.x = cvt_pk_bf16(a[0], a[1]); w.y = cvt_pk_bf16(a[2], a[3]); w.z = cvt_pk_bf16(b[0], b[1]); w.w = cvt_pk_bf16(b[2], b[3]); return w; }
;     __device__ __forceinline__ void operator()(const f32x4 (&acc)[2][2][4][2], const pg8::Unit& u, int wr, int wc, int fr, int fq) const {
; #pragma unroll
;         for (int ai = 0; ai < 2; ++ai)
; #pragma unroll
;             for (int m = 0; m < 4; ++m) { const int row = u.pm * 256 + ai * 128 + wr * 64 + m * 16 + fr; float ss = 0.f;
; #pragma unroll
;                 for (int bj = 0; bj < 2; ++bj) { const int col = u.pn * 256 + bj * 128 + wc * 32 + 8 * fq;
;                     f32x4 x0, x1; unpack_bf16x8(*(const u32x4*)(X2B + (size_t)row * D + col), x0, x1);
;                     const f32x4 v0 = acc[ai][bj][m][0] + x0, v1 = acc[ai][bj][m][1] + x1;
;                     ss += (v0[0] * v0[0] + v0[1] * v0[1]) + (v0[2] * v0[2] + v0[3] * v0[3]) + (v1[0] * v1[0] + v1[1] * v1[1]) + (v1[2] * v1[2] + v1[3] * v1[3]);
;                     *(u32x4*)(X3B + (size_t)row * D + col) = pack8(v0, v1); }
;                 ss += __shfl_xor(ss, 16); ss += __shfl_xor(ss, 32);
;                 if (fq == 0) atomicAdd(rss + row, ss); }
;     }
.LBB0_946:
	s_or_b64 exec, exec, s[20:21]
	v_add_u32_e32 v32, 0xa0, v148
	s_waitcnt lgkmcnt(0)
	v_ashrrev_i32_e32 v33, 31, v32
	v_lshlrev_b64 v[38:39], 11, v[32:33]
	v_lshl_add_u64 v[34:35], s[8:9], 0, v[38:39]
	v_lshl_add_u64 v[40:41], v[34:35], 0, v[146:147]
	s_nop 0
	s_waitcnt vmcnt(15)
	v_lshlrev_b32_e32 v42, 16, v218
	v_and_b32_e32 v43, 0xffff0000, v218
	v_lshlrev_b32_e32 v34, 16, v219
	v_and_b32_e32 v35, 0xffff0000, v219
	v_lshlrev_b32_e32 v44, 16, v220
	v_and_b32_e32 v45, 0xffff0000, v220
	v_lshlrev_b32_e32 v36, 16, v221
	v_and_b32_e32 v37, 0xffff0000, v221
	v_pk_add_f32 v[34:35], v[30:31], v[34:35]
	v_pk_add_f32 v[42:43], v[28:29], v[42:43]
	v_pk_add_f32 v[36:37], v[26:27], v[36:37]
	v_pk_add_f32 v[44:45], v[24:25], v[44:45]
	v_cvt_pk_bf16_f32 v24, v42, v43
	v_cvt_pk_bf16_f32 v25, v34, v35
	v_mul_f32_e32 v35, v35, v35
	v_cvt_pk_bf16_f32 v26, v44, v45
	v_cvt_pk_bf16_f32 v27, v36, v37
	s_nop 0
	v_mul_f32_e32 v40, v43, v43
	v_mul_f32_e32 v41, v45, v45
	v_fmac_f32_e32 v40, v42, v42
	v_fmac_f32_e32 v35, v34, v34
	v_mul_f32_e32 v37, v37, v37
	v_fmac_f32_e32 v41, v44, v44
	v_add_f32_e32 v34, v40, v35
	v_fmac_f32_e32 v37, v36, v36
	v_add_f32_e32 v34, v41, v34
	v_add_f32_e32 v40, v37, v34
	s_waitcnt vmcnt(14)
	v_lshlrev_b32_e32 v34, 16, v222
	v_and_b32_e32 v35, 0xffff0000, v222
	v_lshlrev_b32_e32 v28, 16, v223
	v_and_b32_e32 v29, 0xffff0000, v223
	v_lshlrev_b32_e32 v36, 16, v224
	v_and_b32_e32 v37, 0xffff0000, v224
	v_lshlrev_b32_e32 v30, 16, v225
	v_and_b32_e32 v31, 0xffff0000, v225
	v_pk_add_f32 v[22:23], v[22:23], v[28:29]
	v_pk_add_f32 v[20:21], v[20:21], v[34:35]
	v_pk_add_f32 v[28:29], v[18:19], v[30:31]
	v_pk_add_f32 v[30:31], v[16:17], v[36:37]
	v_mul_f32_e32 v16, v21, v21
	v_mul_f32_e32 v17, v23, v23
	v_mul_f32_e32 v18, v31, v31
	v_fmac_f32_e32 v16, v20, v20
	v_fmac_f32_e32 v17, v22, v22
	v_mul_f32_e32 v19, v29, v29
	v_fmac_f32_e32 v18, v30, v30
	v_add_f32_e32 v16, v16, v17
	v_add_f32_e32 v16, v18, v16
	v_fmac_f32_e32 v19, v28, v28
	v_add_f32_e32 v16, v19, v16
	v_add_f32_e32 v19, v40, v16
	ds_bpermute_b32 v36, v120, v19
	v_lshl_add_u64 v[16:17], s[10:11], 0, v[38:39]
	v_lshl_add_u64 v[34:35], v[16:17], 0, v[146:147]
	global_store_dwordx4 v[34:35], v[24:27], off
	v_cvt_pk_bf16_f32 v18, v20, v21
	s_waitcnt lgkmcnt(0)
	v_add_f32_e32 v16, v19, v36
	ds_bpermute_b32 v17, v114, v16
	v_cvt_pk_bf16_f32 v19, v22, v23
	v_cvt_pk_bf16_f32 v20, v30, v31
	v_cvt_pk_bf16_f32 v21, v28, v29
	global_store_dwordx4 v[34:35], v[18:21], off offset:256
	s_and_saveexec_b64 s[20:21], s[2:3]
	s_cbranch_execz .LBB0_948
	v_lshl_add_u64 v[18:19], v[32:33], 2, s[12:13]
	s_waitcnt lgkmcnt(0)
	v_add_f32_e32 v16, v16, v17
	global_atomic_add_f32 v[18:19], v16, off
.LBB0_948:
	s_or_b64 exec, exec, s[20:21]
	v_add_u32_e32 v16, 0xb0, v148
	s_waitcnt lgkmcnt(0)
	v_ashrrev_i32_e32 v17, 31, v16
	v_lshlrev_b64 v[22:23], 11, v[16:17]
	v_lshl_add_u64 v[18:19], s[8:9], 0, v[22:23]
	v_lshl_add_u64 v[24:25], v[18:19], 0, v[146:147]
	s_nop 0
	s_waitcnt vmcnt(15)
	v_lshlrev_b32_e32 v26, 16, v234
	v_and_b32_e32 v27, 0xffff0000, v234
	v_lshlrev_b32_e32 v18, 16, v235
	v_and_b32_e32 v19, 0xffff0000, v235
	v_lshlrev_b32_e32 v28, 16, v236
	v_and_b32_e32 v29, 0xffff0000, v236
	v_lshlrev_b32_e32 v20, 16, v237
	v_and_b32_e32 v21, 0xffff0000, v237
	v_pk_add_f32 v[18:19], v[14:15], v[18:19]
	v_pk_add_f32 v[26:27], v[12:13], v[26:27]
	v_pk_add_f32 v[20:21], v[10:11], v[20:21]
	v_pk_add_f32 v[28:29], v[8:9], v[28:29]
	v_cvt_pk_bf16_f32 v8, v26, v27
	v_cvt_pk_bf16_f32 v9, v18, v19
	v_mul_f32_e32 v19, v19, v19
	v_cvt_pk_bf16_f32 v10, v28, v29
	v_cvt_pk_bf16_f32 v11, v20, v21
	s_nop 0
	v_mul_f32_e32 v24, v27, v27
	v_mul_f32_e32 v25, v29, v29
	v_fmac_f32_e32 v24, v26, v26
	v_fmac_f32_e32 v19, v18, v18
	v_mul_f32_e32 v21, v21, v21
	v_fmac_f32_e32 v25, v28, v28
	v_add_f32_e32 v18, v24, v19
	v_fmac_f32_e32 v21, v20, v20
	v_add_f32_e32 v18, v25, v18
	v_add_f32_e32 v24, v21, v18
	s_waitcnt vmcnt(14)
	v_lshlrev_b32_e32 v18, 16, v238
	v_and_b32_e32 v19, 0xffff0000, v238
	v_lshlrev_b32_e32 v12, 16, v239
	v_and_b32_e32 v13, 0xffff0000, v239
	v_lshlrev_b32_e32 v20, 16, v240
	v_and_b32_e32 v21, 0xffff0000, v240
	v_lshlrev_b32_e32 v14, 16, v241
	v_and_b32_e32 v15, 0xffff0000, v241
	v_pk_add_f32 v[6:7], v[6:7], v[12:13]
	v_pk_add_f32 v[4:5], v[4:5], v[18:19]
	v_pk_add_f32 v[12:13], v[2:3], v[14:15]
	v_pk_add_f32 v[14:15], v[0:1], v[20:21]
	v_mul_f32_e32 v0, v5, v5
	v_mul_f32_e32 v1, v7, v7
	v_mul_f32_e32 v2, v15, v15
	v_fmac_f32_e32 v0, v4, v4
	v_fmac_f32_e32 v1, v6, v6
	v_mul_f32_e32 v3, v13, v13
	v_fmac_f32_e32 v2, v14, v14
	v_add_f32_e32 v0, v0, v1
	v_add_f32_e32 v0, v2, v0
	v_fmac_f32_e32 v3, v12, v12
	v_add_f32_e32 v0, v3, v0
	v_add_f32_e32 v3, v24, v0
	ds_bpermute_b32 v20, v120, v3
	v_lshl_add_u64 v[0:1], s[10:11], 0, v[22:23]
	v_lshl_add_u64 v[18:19], v[0:1], 0, v[146:147]
	global_store_dwordx4 v[18:19], v[8:11], off
	v_cvt_pk_bf16_f32 v2, v4, v5
	s_waitcnt lgkmcnt(0)
	v_add_f32_e32 v0, v3, v20
	ds_bpermute_b32 v1, v114, v0
	v_cvt_pk_bf16_f32 v3, v6, v7
	v_cvt_pk_bf16_f32 v4, v14, v15
	v_cvt_pk_bf16_f32 v5, v12, v13
	global_store_dwordx4 v[18:19], v[2:5], off offset:256
	s_and_saveexec_b64 s[20:21], s[2:3]
	s_cbranch_execz .LBB0_950
	v_lshl_add_u64 v[2:3], v[16:17], 2, s[12:13]
	s_waitcnt lgkmcnt(0)
	v_add_f32_e32 v0, v0, v1
	global_atomic_add_f32 v[2:3], v0, off
